# snake MFMA order inside each 8-MFMA group so consecutive MFMAs share one operand (plus 8-byte aligned MFMA runs)
# speedup vs baseline: 1.0027x; 1.0027x over previous
; #define PG8_STAGE(bufoff, gbase, voff) do { _Pragma("unroll") for (int _i = 0; _i < 2; ++_i) \
;         __builtin_amdgcn_global_load_lds((const unsigned*)((const char*)(gbase) + (voff)[_i]), (LAS unsigned*)(lds + (bufoff) + ldsw + _i * 8192), 16, 0, 0); } while (0)
; #define PG8_LDA(dst, b, h) do { _Pragma("unroll") for (int m = 0; m < 4; ++m) _Pragma("unroll") for (int k = 0; k < 2; ++k) dst[m][k] = *(const LAS bf16x8*)(lds + PG8_SA(b, h) + aoff + m * 2048 + k * 1024); } while (0)
; #define PG8_LDB(dst, b, h) do { _Pragma("unroll") for (int n = 0; n < 2; ++n) _Pragma("unroll") for (int k = 0; k < 2; ++k) dst[n][k] = *(const LAS bf16x8*)(lds + PG8_SB(b, h) + boff + n * 2048 + k * 1024); } while (0)
; #define PG8_MMA(ai, bj, At, Bt) do { __builtin_amdgcn_s_setprio(1); _Pragma("unroll") for (int m = 0; m < 4; ++m) _Pragma("unroll") for (int n = 0; n < 2; ++n) _Pragma("unroll") for (int k = 0; k < 2; ++k) \
;         acc[ai][bj][m][n] = __builtin_amdgcn_mfma_f32_16x16x32_bf16(Bt[n][k], At[m][k], acc[ai][bj][m][n], 0, 0, 0); __builtin_amdgcn_s_setprio(0); } while (0)
; #define PG8_WAIT_V(n) asm volatile("s_waitcnt vmcnt(" #n ")" ::: "memory")
; #define PG8_WAIT_L(n) asm volatile("s_waitcnt lgkmcnt(" #n ")" ::: "memory")
; #define PG8_BAR __builtin_amdgcn_s_barrier()
; #define PG8_SCHED __builtin_amdgcn_sched_barrier(0)
; template <int FIXED_NT  , class Epi, class Sched>
; __device__ __forceinline__ void gemm_phase(LAS unsigned char* lds, const int tid_in, const int lda, const int ldb, const Sched& S, const Epi& E) {
;     ...
;         for (int t = 0; t < nt; t += 2) {
;             const bool last = (t == nt - 2);
;             const char* a1 = cA + (size_t)(t + 1) * kstep;
;             const char* a2 = last ? nA : cA + (size_t)(t + 2) * kstep; const char* b2 = last ? nB : cB + (size_t)(t + 2) * kstep;
;             const char* a3 = a2 + kstep; const char* b3 = b2 + kstep;
;             PG8_LDB(B0, 0, 0); PG8_LDB(B1, 0, 1); PG8_SCHED; PG8_LDA(At, 0, 0); PG8_STAGE(PG8_SA(1, 1), a1 + hstepA, voffA);
;             PG8_WAIT_V(8); PG8_WAIT_L(0); PG8_BAR; PG8_MMA(0, 0, At, B0); PG8_MMA(0, 1, At, B1); PG8_BAR; PG8_SCHED;
;             PG8_LDA(At, 0, 1); PG8_STAGE(PG8_SB(0, 0), b2, voffB); PG8_STAGE(PG8_SB(0, 1), b2 + hstepB, voffB); PG8_STAGE(PG8_SA(0, 0), a2, voffA);
.LBB0_244:
	s_waitcnt lgkmcnt(0)
	ds_read_b128 v[128:131], v183
	ds_read_b128 v[132:135], v183 offset:1024
	ds_read_b128 v[136:139], v183 offset:2048
	ds_read_b128 v[140:143], v183 offset:3072
	ds_read_b128 v[162:165], v184
	ds_read_b128 v[188:191], v184 offset:1024
	ds_read_b128 v[192:195], v184 offset:2048
	ds_read_b128 v[196:199], v184 offset:3072
	s_add_i32 s79, s57, 2
	s_add_u32 s24, s6, 0xfff80080
	s_addc_u32 s25, s7, -1
	s_cmp_eq_u32 s87, s57
	s_cselect_b32 s65, s59, s25
	s_cselect_b32 s64, s58, s24
	s_cselect_b32 s63, s61, s53
	s_cselect_b32 s62, s60, s14
	v_lshl_add_u64 v[166:167], s[6:7], 0, v[158:159]
	s_add_i32 m0, s67, 0xc000
	ds_read_b128 v[200:203], v185
	ds_read_b128 v[204:207], v185 offset:1024
	ds_read_b128 v[208:211], v185 offset:2048
	ds_read_b128 v[212:215], v185 offset:3072
	ds_read_b128 v[216:219], v185 offset:4096
	ds_read_b128 v[220:223], v185 offset:5120
	ds_read_b128 v[226:229], v185 offset:6144
	ds_read_b128 v[230:233], v185 offset:7168
	global_load_lds_dwordx4 v[166:167], off
	v_lshl_add_u64 v[166:167], s[6:7], 0, v[160:161]
	s_add_i32 m0, s67, 0xe000
	s_nop 0
	global_load_lds_dwordx4 v[166:167], off
	s_waitcnt vmcnt(8)
	s_waitcnt lgkmcnt(0)
	s_barrier
	s_setprio 1
	s_waitcnt lgkmcnt(0)
	v_mfma_f32_16x16x32_bf16 v[124:127], v[128:131], v[200:203], v[124:127]
	v_mfma_f32_16x16x32_bf16 v[120:123], v[136:139], v[200:203], v[120:123]
	v_mfma_f32_16x16x32_bf16 v[104:107], v[136:139], v[208:211], v[104:107]
	v_mfma_f32_16x16x32_bf16 v[108:111], v[128:131], v[208:211], v[108:111]
	v_mfma_f32_16x16x32_bf16 v[92:95], v[128:131], v[216:219], v[92:95]
	v_mfma_f32_16x16x32_bf16 v[88:91], v[136:139], v[216:219], v[88:91]
	v_mfma_f32_16x16x32_bf16 v[72:75], v[136:139], v[226:229], v[72:75]
	v_mfma_f32_16x16x32_bf16 v[76:79], v[128:131], v[226:229], v[76:79]
	v_mfma_f32_16x16x32_bf16 v[124:127], v[132:135], v[204:207], v[124:127]
	v_mfma_f32_16x16x32_bf16 v[120:123], v[140:143], v[204:207], v[120:123]
	v_mfma_f32_16x16x32_bf16 v[104:107], v[140:143], v[212:215], v[104:107]
	v_mfma_f32_16x16x32_bf16 v[108:111], v[132:135], v[212:215], v[108:111]
	v_mfma_f32_16x16x32_bf16 v[92:95], v[132:135], v[220:223], v[92:95]
	v_mfma_f32_16x16x32_bf16 v[88:91], v[140:143], v[220:223], v[88:91]
	v_mfma_f32_16x16x32_bf16 v[72:75], v[140:143], v[230:233], v[72:75]
	v_mfma_f32_16x16x32_bf16 v[76:79], v[132:135], v[230:233], v[76:79]
	s_setprio 0
	s_setprio 1
	v_mfma_f32_16x16x32_bf16 v[116:119], v[162:165], v[200:203], v[116:119]
	v_mfma_f32_16x16x32_bf16 v[112:115], v[192:195], v[200:203], v[112:115]
	v_mfma_f32_16x16x32_bf16 v[96:99], v[192:195], v[208:211], v[96:99]
	v_mfma_f32_16x16x32_bf16 v[100:103], v[162:165], v[208:211], v[100:103]
	v_mfma_f32_16x16x32_bf16 v[84:87], v[162:165], v[216:219], v[84:87]
	v_mfma_f32_16x16x32_bf16 v[80:83], v[192:195], v[216:219], v[80:83]
	v_mfma_f32_16x16x32_bf16 v[64:67], v[192:195], v[226:229], v[64:67]
	v_mfma_f32_16x16x32_bf16 v[68:71], v[162:165], v[226:229], v[68:71]
	v_mfma_f32_16x16x32_bf16 v[116:119], v[188:191], v[204:207], v[116:119]
	v_mfma_f32_16x16x32_bf16 v[112:115], v[196:199], v[204:207], v[112:115]
	v_mfma_f32_16x16x32_bf16 v[96:99], v[196:199], v[212:215], v[96:99]
	v_mfma_f32_16x16x32_bf16 v[100:103], v[188:191], v[212:215], v[100:103]
	v_mfma_f32_16x16x32_bf16 v[84:87], v[188:191], v[220:223], v[84:87]
	v_mfma_f32_16x16x32_bf16 v[80:83], v[196:199], v[220:223], v[80:83]
	v_mfma_f32_16x16x32_bf16 v[64:67], v[196:199], v[230:233], v[64:67]
	v_mfma_f32_16x16x32_bf16 v[68:71], v[188:191], v[230:233], v[68:71]
	s_setprio 0
	s_barrier
	s_add_i32 s24, s92, s66
	v_lshl_add_u64 v[166:167], s[62:63], 0, v[146:147]
	s_mov_b32 m0, s24
	ds_read_b128 v[200:203], v185 offset:16384
	ds_read_b128 v[204:207], v185 offset:17408
	ds_read_b128 v[208:211], v185 offset:18432
	ds_read_b128 v[212:215], v185 offset:19456
	ds_read_b128 v[216:219], v185 offset:20480
	ds_read_b128 v[220:223], v185 offset:21504
	ds_read_b128 v[226:229], v185 offset:22528
	ds_read_b128 v[230:233], v185 offset:23552
	global_load_lds_dwordx4 v[166:167], off
	s_add_i32 m0, s24, 0x2000
	s_add_u32 vcc_lo, s62, 0x80000
	v_lshl_add_u64 v[234:235], s[62:63], 0, v[150:151]
	s_addc_u32 vcc_hi, s63, 0
	s_add_i32 s24, s93, s66
	global_load_lds_dwordx4 v[234:235], off
	v_lshl_add_u64 v[236:237], vcc, 0, v[146:147]
	s_mov_b32 m0, s24
	v_lshl_add_u64 v[238:239], s[64:65], 0, v[148:149]
	global_load_lds_dwordx4 v[236:237], off
	v_lshl_add_u64 v[236:237], vcc, 0, v[150:151]
	s_add_i32 m0, s24, 0x2000
	s_nop 0
	global_load_lds_dwordx4 v[236:237], off
	v_lshl_add_u64 v[236:237], s[64:65], 0, v[144:145]
	s_mov_b32 m0, s67
	s_nop 0
	global_load_lds_dwordx4 v[236:237], off
	s_mov_b32 m0, s68
	s_nop 0
	global_load_lds_dwordx4 v[238:239], off
	s_nop 0
	s_waitcnt vmcnt(8)
	s_waitcnt lgkmcnt(0)
	s_barrier
; #define PG8_STAGE(bufoff, gbase, voff) do { _Pragma("unroll") for (int _i = 0; _i < 2; ++_i) \
;         __builtin_amdgcn_global_load_lds((const unsigned*)((const char*)(gbase) + (voff)[_i]), (LAS unsigned*)(lds + (bufoff) + ldsw + _i * 8192), 16, 0, 0); } while (0)
; #define PG8_LDA(dst, b, h) do { _Pragma("unroll") for (int m = 0; m < 4; ++m) _Pragma("unroll") for (int k = 0; k < 2; ++k) dst[m][k] = *(const LAS bf16x8*)(lds + PG8_SA(b, h) + aoff + m * 2048 + k * 1024); } while (0)
; #define PG8_LDB(dst, b, h) do { _Pragma("unroll") for (int n = 0; n < 2; ++n) _Pragma("unroll") for (int k = 0; k < 2; ++k) dst[n][k] = *(const LAS bf16x8*)(lds + PG8_SB(b, h) + boff + n * 2048 + k * 1024); } while (0)
; #define PG8_MMA(ai, bj, At, Bt) do { __builtin_amdgcn_s_setprio(1); _Pragma("unroll") for (int m = 0; m < 4; ++m) _Pragma("unroll") for (int n = 0; n < 2; ++n) _Pragma("unroll") for (int k = 0; k < 2; ++k) \
;         acc[ai][bj][m][n] = __builtin_amdgcn_mfma_f32_16x16x32_bf16(Bt[n][k], At[m][k], acc[ai][bj][m][n], 0, 0, 0); __builtin_amdgcn_s_setprio(0); } while (0)
; #define PG8_WAIT_V(n) asm volatile("s_waitcnt vmcnt(" #n ")" ::: "memory")
; #define PG8_WAIT_L(n) asm volatile("s_waitcnt lgkmcnt(" #n ")" ::: "memory")
; #define PG8_BAR __builtin_amdgcn_s_barrier()
; #define PG8_SCHED __builtin_amdgcn_sched_barrier(0)
; template <int FIXED_NT  , class Epi, class Sched>
; __device__ __forceinline__ void gemm_phase(LAS unsigned char* lds, const int tid_in, const int lda, const int ldb, const Sched& S, const Epi& E) {
;     ...
;             PG8_WAIT_V(8); PG8_WAIT_L(0); PG8_BAR; PG8_MMA(1, 0, At, B0); PG8_MMA(1, 1, At, B1); PG8_BAR; PG8_SCHED;
;             PG8_LDB(B0, 1, 0); PG8_LDB(B1, 1, 1); PG8_SCHED; PG8_LDA(At, 1, 0); PG8_STAGE(PG8_SA(0, 1), a2 + hstepA, voffA);
;             PG8_WAIT_V(8); PG8_WAIT_L(0); PG8_BAR; PG8_MMA(0, 0, At, B0); PG8_MMA(0, 1, At, B1); PG8_BAR; PG8_SCHED;
	s_setprio 1
	s_waitcnt lgkmcnt(0)
	v_mfma_f32_16x16x32_bf16 v[60:63], v[128:131], v[200:203], v[60:63]
	v_mfma_f32_16x16x32_bf16 v[56:59], v[136:139], v[200:203], v[56:59]
	v_mfma_f32_16x16x32_bf16 v[40:43], v[136:139], v[208:211], v[40:43]
	v_mfma_f32_16x16x32_bf16 v[44:47], v[128:131], v[208:211], v[44:47]
	v_mfma_f32_16x16x32_bf16 v[28:31], v[128:131], v[216:219], v[28:31]
	v_mfma_f32_16x16x32_bf16 v[24:27], v[136:139], v[216:219], v[24:27]
	v_mfma_f32_16x16x32_bf16 v[8:11], v[136:139], v[226:229], v[8:11]
	v_mfma_f32_16x16x32_bf16 v[12:15], v[128:131], v[226:229], v[12:15]
	v_mfma_f32_16x16x32_bf16 v[60:63], v[132:135], v[204:207], v[60:63]
	v_mfma_f32_16x16x32_bf16 v[56:59], v[140:143], v[204:207], v[56:59]
	v_mfma_f32_16x16x32_bf16 v[40:43], v[140:143], v[212:215], v[40:43]
	v_mfma_f32_16x16x32_bf16 v[44:47], v[132:135], v[212:215], v[44:47]
	v_mfma_f32_16x16x32_bf16 v[28:31], v[132:135], v[220:223], v[28:31]
	v_mfma_f32_16x16x32_bf16 v[24:27], v[140:143], v[220:223], v[24:27]
	v_mfma_f32_16x16x32_bf16 v[8:11], v[140:143], v[230:233], v[8:11]
	v_mfma_f32_16x16x32_bf16 v[12:15], v[132:135], v[230:233], v[12:15]
	s_setprio 0
	s_setprio 1
	v_mfma_f32_16x16x32_bf16 v[52:55], v[162:165], v[200:203], v[52:55]
	v_mfma_f32_16x16x32_bf16 v[48:51], v[192:195], v[200:203], v[48:51]
	v_mfma_f32_16x16x32_bf16 v[32:35], v[192:195], v[208:211], v[32:35]
	v_mfma_f32_16x16x32_bf16 v[36:39], v[162:165], v[208:211], v[36:39]
	v_mfma_f32_16x16x32_bf16 v[20:23], v[162:165], v[216:219], v[20:23]
	v_mfma_f32_16x16x32_bf16 v[16:19], v[192:195], v[216:219], v[16:19]
	v_mfma_f32_16x16x32_bf16 v[0:3], v[192:195], v[226:229], v[0:3]
	v_mfma_f32_16x16x32_bf16 v[4:7], v[162:165], v[226:229], v[4:7]
	v_mfma_f32_16x16x32_bf16 v[52:55], v[188:191], v[204:207], v[52:55]
	v_mfma_f32_16x16x32_bf16 v[48:51], v[196:199], v[204:207], v[48:51]
	v_mfma_f32_16x16x32_bf16 v[32:35], v[196:199], v[212:215], v[32:35]
	v_mfma_f32_16x16x32_bf16 v[36:39], v[188:191], v[212:215], v[36:39]
	v_mfma_f32_16x16x32_bf16 v[20:23], v[188:191], v[220:223], v[20:23]
	v_mfma_f32_16x16x32_bf16 v[16:19], v[196:199], v[220:223], v[16:19]
	v_mfma_f32_16x16x32_bf16 v[0:3], v[196:199], v[230:233], v[0:3]
	v_mfma_f32_16x16x32_bf16 v[4:7], v[188:191], v[230:233], v[4:7]
	s_setprio 0
	s_barrier
	s_add_i32 s24, 0, 0x18000
	s_add_i32 s25, 0, 0x1c000
	v_add_u32_e32 v140, s24, v168
	v_add_u32_e32 v152, s25, v168
	ds_read_b128 v[128:131], v140
	ds_read_b128 v[132:135], v140 offset:1024
	ds_read_b128 v[136:139], v140 offset:2048
	ds_read_b128 v[140:143], v140 offset:3072
	ds_read_b128 v[162:165], v152
	ds_read_b128 v[188:191], v152 offset:1024
	ds_read_b128 v[192:195], v152 offset:2048
	ds_read_b128 v[196:199], v152 offset:3072
	s_add_u32 s64, s64, 0x80000
	s_addc_u32 s65, s65, 0
	s_mov_b32 m0, s69
	v_lshl_add_u64 v[240:241], s[64:65], 0, v[144:145]
	ds_read_b128 v[200:203], v185 offset:32768
	ds_read_b128 v[204:207], v185 offset:33792
	ds_read_b128 v[208:211], v185 offset:34816
	ds_read_b128 v[212:215], v185 offset:35840
	ds_read_b128 v[216:219], v185 offset:36864
	ds_read_b128 v[220:223], v185 offset:37888
	ds_read_b128 v[226:229], v185 offset:38912
	ds_read_b128 v[230:233], v185 offset:39936
	global_load_lds_dwordx4 v[240:241], off
	v_lshl_add_u64 v[240:241], s[64:65], 0, v[148:149]
	s_mov_b32 m0, s70
	s_nop 0
	global_load_lds_dwordx4 v[240:241], off
	s_nop 0
	s_waitcnt vmcnt(8)
	s_waitcnt lgkmcnt(0)
	s_barrier
	s_setprio 1
	s_waitcnt lgkmcnt(0)
	v_mfma_f32_16x16x32_bf16 v[124:127], v[128:131], v[200:203], v[124:127]
	v_mfma_f32_16x16x32_bf16 v[120:123], v[136:139], v[200:203], v[120:123]
	v_mfma_f32_16x16x32_bf16 v[104:107], v[136:139], v[208:211], v[104:107]
	v_mfma_f32_16x16x32_bf16 v[108:111], v[128:131], v[208:211], v[108:111]
	v_mfma_f32_16x16x32_bf16 v[92:95], v[128:131], v[216:219], v[92:95]
	v_mfma_f32_16x16x32_bf16 v[88:91], v[136:139], v[216:219], v[88:91]
	v_mfma_f32_16x16x32_bf16 v[72:75], v[136:139], v[226:229], v[72:75]
	v_mfma_f32_16x16x32_bf16 v[76:79], v[128:131], v[226:229], v[76:79]
	v_mfma_f32_16x16x32_bf16 v[124:127], v[132:135], v[204:207], v[124:127]
	v_mfma_f32_16x16x32_bf16 v[120:123], v[140:143], v[204:207], v[120:123]
	v_mfma_f32_16x16x32_bf16 v[104:107], v[140:143], v[212:215], v[104:107]
	v_mfma_f32_16x16x32_bf16 v[108:111], v[132:135], v[212:215], v[108:111]
	v_mfma_f32_16x16x32_bf16 v[92:95], v[132:135], v[220:223], v[92:95]
	v_mfma_f32_16x16x32_bf16 v[88:91], v[140:143], v[220:223], v[88:91]
	v_mfma_f32_16x16x32_bf16 v[72:75], v[140:143], v[230:233], v[72:75]
	v_mfma_f32_16x16x32_bf16 v[76:79], v[132:135], v[230:233], v[76:79]
	s_setprio 0
	s_setprio 1
	v_mfma_f32_16x16x32_bf16 v[116:119], v[162:165], v[200:203], v[116:119]
	v_mfma_f32_16x16x32_bf16 v[112:115], v[192:195], v[200:203], v[112:115]
	v_mfma_f32_16x16x32_bf16 v[96:99], v[192:195], v[208:211], v[96:99]
	v_mfma_f32_16x16x32_bf16 v[100:103], v[162:165], v[208:211], v[100:103]
	v_mfma_f32_16x16x32_bf16 v[84:87], v[162:165], v[216:219], v[84:87]
	v_mfma_f32_16x16x32_bf16 v[80:83], v[192:195], v[216:219], v[80:83]
	v_mfma_f32_16x16x32_bf16 v[64:67], v[192:195], v[226:229], v[64:67]
	v_mfma_f32_16x16x32_bf16 v[68:71], v[162:165], v[226:229], v[68:71]
	v_mfma_f32_16x16x32_bf16 v[116:119], v[188:191], v[204:207], v[116:119]
	v_mfma_f32_16x16x32_bf16 v[112:115], v[196:199], v[204:207], v[112:115]
	v_mfma_f32_16x16x32_bf16 v[96:99], v[196:199], v[212:215], v[96:99]
	v_mfma_f32_16x16x32_bf16 v[100:103], v[188:191], v[212:215], v[100:103]
	v_mfma_f32_16x16x32_bf16 v[84:87], v[188:191], v[220:223], v[84:87]
	v_mfma_f32_16x16x32_bf16 v[80:83], v[196:199], v[220:223], v[80:83]
	v_mfma_f32_16x16x32_bf16 v[64:67], v[196:199], v[230:233], v[64:67]
	v_mfma_f32_16x16x32_bf16 v[68:71], v[188:191], v[230:233], v[68:71]
	s_setprio 0
	s_barrier
; #define PG8_STAGE(bufoff, gbase, voff) do { _Pragma("unroll") for (int _i = 0; _i < 2; ++_i) \
;         __builtin_amdgcn_global_load_lds((const unsigned*)((const char*)(gbase) + (voff)[_i]), (LAS unsigned*)(lds + (bufoff) + ldsw + _i * 8192), 16, 0, 0); } while (0)
; #define PG8_LDA(dst, b, h) do { _Pragma("unroll") for (int m = 0; m < 4; ++m) _Pragma("unroll") for (int k = 0; k < 2; ++k) dst[m][k] = *(const LAS bf16x8*)(lds + PG8_SA(b, h) + aoff + m * 2048 + k * 1024); } while (0)
; #define PG8_MMA(ai, bj, At, Bt) do { __builtin_amdgcn_s_setprio(1); _Pragma("unroll") for (int m = 0; m < 4; ++m) _Pragma("unroll") for (int n = 0; n < 2; ++n) _Pragma("unroll") for (int k = 0; k < 2; ++k) \
;         acc[ai][bj][m][n] = __builtin_amdgcn_mfma_f32_16x16x32_bf16(Bt[n][k], At[m][k], acc[ai][bj][m][n], 0, 0, 0); __builtin_amdgcn_s_setprio(0); } while (0)
; #define PG8_WAIT_V(n) asm volatile("s_waitcnt vmcnt(" #n ")" ::: "memory")
; #define PG8_WAIT_L(n) asm volatile("s_waitcnt lgkmcnt(" #n ")" ::: "memory")
; #define PG8_BAR __builtin_amdgcn_s_barrier()
; #define PG8_SCHED __builtin_amdgcn_sched_barrier(0)
; template <int FIXED_NT  , class Epi, class Sched>
; __device__ __forceinline__ void gemm_phase(LAS unsigned char* lds, const int tid_in, const int lda, const int ldb, const Sched& S, const Epi& E) {
;     ...
;             PG8_LDA(At, 1, 1); PG8_STAGE(PG8_SB(1, 0), b3, voffB); PG8_STAGE(PG8_SB(1, 1), b3 + hstepB, voffB); PG8_STAGE(PG8_SA(1, 0), a3, voffA);
;             PG8_WAIT_V(8); PG8_WAIT_L(0); PG8_BAR; PG8_MMA(1, 0, At, B0); PG8_MMA(1, 1, At, B1); PG8_BAR; PG8_SCHED;
;         }
	s_add_i32 s24, s24, s66
	v_lshl_add_u64 v[166:167], v[166:167], 0, s[18:19]
	s_mov_b32 m0, s24
	ds_read_b128 v[200:203], v185 offset:49152
	ds_read_b128 v[204:207], v185 offset:50176
	ds_read_b128 v[208:211], v185 offset:51200
	ds_read_b128 v[212:215], v185 offset:52224
	ds_read_b128 v[216:219], v185 offset:53248
	ds_read_b128 v[220:223], v185 offset:54272
	ds_read_b128 v[226:229], v185 offset:55296
	ds_read_b128 v[230:233], v185 offset:56320
	global_load_lds_dwordx4 v[166:167], off
	s_add_i32 m0, s24, 0x2000
	s_add_u32 s62, s62, 0x80080
	v_lshl_add_u64 v[166:167], v[234:235], 0, s[18:19]
	s_addc_u32 s63, s63, 0
	s_add_i32 s24, s25, s66
	global_load_lds_dwordx4 v[166:167], off
	v_lshl_add_u64 v[166:167], s[62:63], 0, v[146:147]
	s_mov_b32 m0, s24
	s_nop 0
	global_load_lds_dwordx4 v[166:167], off
	v_lshl_add_u64 v[166:167], s[62:63], 0, v[150:151]
	s_add_i32 m0, s24, 0x2000
	s_nop 0
	global_load_lds_dwordx4 v[166:167], off
	v_lshl_add_u64 v[166:167], v[236:237], 0, s[18:19]
	s_mov_b32 m0, s72
	s_nop 0
	global_load_lds_dwordx4 v[166:167], off
	v_lshl_add_u64 v[166:167], v[238:239], 0, s[18:19]
	s_mov_b32 m0, s73
	s_nop 0
	global_load_lds_dwordx4 v[166:167], off
	s_waitcnt vmcnt(8)
	s_waitcnt lgkmcnt(0)
	s_barrier
	s_setprio 1
	s_waitcnt lgkmcnt(0)
	v_mfma_f32_16x16x32_bf16 v[60:63], v[128:131], v[200:203], v[60:63]
	v_mfma_f32_16x16x32_bf16 v[56:59], v[136:139], v[200:203], v[56:59]
	v_mfma_f32_16x16x32_bf16 v[40:43], v[136:139], v[208:211], v[40:43]
	v_mfma_f32_16x16x32_bf16 v[44:47], v[128:131], v[208:211], v[44:47]
	v_mfma_f32_16x16x32_bf16 v[28:31], v[128:131], v[216:219], v[28:31]
	v_mfma_f32_16x16x32_bf16 v[24:27], v[136:139], v[216:219], v[24:27]
	v_mfma_f32_16x16x32_bf16 v[8:11], v[136:139], v[226:229], v[8:11]
	v_mfma_f32_16x16x32_bf16 v[12:15], v[128:131], v[226:229], v[12:15]
	v_mfma_f32_16x16x32_bf16 v[60:63], v[132:135], v[204:207], v[60:63]
	v_mfma_f32_16x16x32_bf16 v[56:59], v[140:143], v[204:207], v[56:59]
	v_mfma_f32_16x16x32_bf16 v[40:43], v[140:143], v[212:215], v[40:43]
	v_mfma_f32_16x16x32_bf16 v[44:47], v[132:135], v[212:215], v[44:47]
	v_mfma_f32_16x16x32_bf16 v[28:31], v[132:135], v[220:223], v[28:31]
	v_mfma_f32_16x16x32_bf16 v[24:27], v[140:143], v[220:223], v[24:27]
	v_mfma_f32_16x16x32_bf16 v[8:11], v[140:143], v[230:233], v[8:11]
	v_mfma_f32_16x16x32_bf16 v[12:15], v[132:135], v[230:233], v[12:15]
	s_setprio 0
	s_setprio 1
	v_mfma_f32_16x16x32_bf16 v[52:55], v[162:165], v[200:203], v[52:55]
	v_mfma_f32_16x16x32_bf16 v[48:51], v[192:195], v[200:203], v[48:51]
	v_mfma_f32_16x16x32_bf16 v[32:35], v[192:195], v[208:211], v[32:35]
	v_mfma_f32_16x16x32_bf16 v[36:39], v[162:165], v[208:211], v[36:39]
	v_mfma_f32_16x16x32_bf16 v[20:23], v[162:165], v[216:219], v[20:23]
	v_mfma_f32_16x16x32_bf16 v[16:19], v[192:195], v[216:219], v[16:19]
	v_mfma_f32_16x16x32_bf16 v[0:3], v[192:195], v[226:229], v[0:3]
	v_mfma_f32_16x16x32_bf16 v[4:7], v[162:165], v[226:229], v[4:7]
	v_mfma_f32_16x16x32_bf16 v[52:55], v[188:191], v[204:207], v[52:55]
	v_mfma_f32_16x16x32_bf16 v[48:51], v[196:199], v[204:207], v[48:51]
	v_mfma_f32_16x16x32_bf16 v[32:35], v[196:199], v[212:215], v[32:35]
	v_mfma_f32_16x16x32_bf16 v[36:39], v[188:191], v[212:215], v[36:39]
	v_mfma_f32_16x16x32_bf16 v[20:23], v[188:191], v[220:223], v[20:23]
	v_mfma_f32_16x16x32_bf16 v[16:19], v[196:199], v[220:223], v[16:19]
	v_mfma_f32_16x16x32_bf16 v[0:3], v[196:199], v[230:233], v[0:3]
	v_mfma_f32_16x16x32_bf16 v[4:7], v[188:191], v[230:233], v[4:7]
	s_setprio 0
	s_barrier
	s_add_u32 s6, s6, 0x100
	s_addc_u32 s7, s7, 0
	s_add_u32 s14, s14, 0x100
	s_addc_u32 s53, s53, 0
	s_cmp_ge_i32 s79, s35
	s_mov_b32 s57, s79
	s_cbranch_scc0 .LBB0_244
	s_and_b64 vcc, exec, s[22:23]
	s_cbranch_vccz .LBB0_250

; #define PG8_STAGE(bufoff, gbase, voff) do { _Pragma("unroll") for (int _i = 0; _i < 2; ++_i) \
;         __builtin_amdgcn_global_load_lds((const unsigned*)((const char*)(gbase) + (voff)[_i]), (LAS unsigned*)(lds + (bufoff) + ldsw + _i * 8192), 16, 0, 0); } while (0)
; #define PG8_LDA(dst, b, h) do { _Pragma("unroll") for (int m = 0; m < 4; ++m) _Pragma("unroll") for (int k = 0; k < 2; ++k) dst[m][k] = *(const LAS bf16x8*)(lds + PG8_SA(b, h) + aoff + m * 2048 + k * 1024); } while (0)
; #define PG8_LDB(dst, b, h) do { _Pragma("unroll") for (int n = 0; n < 2; ++n) _Pragma("unroll") for (int k = 0; k < 2; ++k) dst[n][k] = *(const LAS bf16x8*)(lds + PG8_SB(b, h) + boff + n * 2048 + k * 1024); } while (0)
; #define PG8_MMA(ai, bj, At, Bt) do { __builtin_amdgcn_s_setprio(1); _Pragma("unroll") for (int m = 0; m < 4; ++m) _Pragma("unroll") for (int n = 0; n < 2; ++n) _Pragma("unroll") for (int k = 0; k < 2; ++k) \
;         acc[ai][bj][m][n] = __builtin_amdgcn_mfma_f32_16x16x32_bf16(Bt[n][k], At[m][k], acc[ai][bj][m][n], 0, 0, 0); __builtin_amdgcn_s_setprio(0); } while (0)
; #define PG8_WAIT_V(n) asm volatile("s_waitcnt vmcnt(" #n ")" ::: "memory")
; #define PG8_WAIT_L(n) asm volatile("s_waitcnt lgkmcnt(" #n ")" ::: "memory")
; #define PG8_BAR __builtin_amdgcn_s_barrier()
; #define PG8_SCHED __builtin_amdgcn_sched_barrier(0)
; template <int FIXED_NT  , class Epi, class Sched>
; __device__ __forceinline__ void gemm_phase(LAS unsigned char* lds, const int tid_in, const int lda, const int ldb, const Sched& S, const Epi& E) {
;     ...
;         for (int t = 0; t < nt; t += 2) {
;             const bool last = (t == nt - 2);
;             const char* a1 = cA + (size_t)(t + 1) * kstep;
;             const char* a2 = last ? nA : cA + (size_t)(t + 2) * kstep; const char* b2 = last ? nB : cB + (size_t)(t + 2) * kstep;
;             const char* a3 = a2 + kstep; const char* b3 = b2 + kstep;
;             PG8_LDB(B0, 0, 0); PG8_LDB(B1, 0, 1); PG8_SCHED; PG8_LDA(At, 0, 0); PG8_STAGE(PG8_SA(1, 1), a1 + hstepA, voffA);
;             PG8_WAIT_V(8); PG8_WAIT_L(0); PG8_BAR; PG8_MMA(0, 0, At, B0); PG8_MMA(0, 1, At, B1); PG8_BAR; PG8_SCHED;
;             PG8_LDA(At, 0, 1); PG8_STAGE(PG8_SB(0, 0), b2, voffB); PG8_STAGE(PG8_SB(0, 1), b2 + hstepB, voffB); PG8_STAGE(PG8_SA(0, 0), a2, voffA);
.LBB0_598:
	ds_read_b128 v[128:131], v167
	ds_read_b128 v[132:135], v167 offset:1024
	ds_read_b128 v[148:151], v167 offset:2048
	ds_read_b128 v[152:155], v167 offset:3072
	ds_read_b128 v[156:159], v168
	ds_read_b128 v[160:163], v168 offset:1024
	ds_read_b128 v[170:173], v168 offset:2048
	ds_read_b128 v[174:177], v168 offset:3072
	s_add_i32 s73, s30, 2
	s_add_u32 s31, s28, 0xfffc0080
	s_addc_u32 s54, s29, -1
	s_cmp_eq_u32 s64, s30
	s_cselect_b32 s30, s22, s17
	s_cselect_b32 s55, s21, s54
	s_cselect_b32 s54, s20, s31
	s_cselect_b32 s31, s23, s72
	s_mov_b32 m0, s65
	v_lshl_add_u64 v[210:211], s[28:29], 0, v[144:145]
	ds_read_b128 v[178:181], v169
	ds_read_b128 v[182:185], v169 offset:1024
	ds_read_b128 v[186:189], v169 offset:2048
	ds_read_b128 v[190:193], v169 offset:3072
	ds_read_b128 v[194:197], v169 offset:4096
	ds_read_b128 v[198:201], v169 offset:5120
	ds_read_b128 v[202:205], v169 offset:6144
	ds_read_b128 v[206:209], v169 offset:7168
	global_load_lds_dwordx4 v[210:211], off
	v_lshl_add_u64 v[210:211], s[28:29], 0, v[146:147]
	s_mov_b32 m0, s66
	s_nop 0
	global_load_lds_dwordx4 v[210:211], off
	s_nop 0
	s_waitcnt vmcnt(8)
	s_waitcnt lgkmcnt(0)
	s_barrier
	s_setprio 1
	s_waitcnt lgkmcnt(0)
	v_mfma_f32_16x16x32_bf16 v[124:127], v[128:131], v[178:181], v[124:127]
	v_mfma_f32_16x16x32_bf16 v[120:123], v[148:151], v[178:181], v[120:123]
	v_mfma_f32_16x16x32_bf16 v[112:115], v[148:151], v[186:189], v[112:115]
	v_mfma_f32_16x16x32_bf16 v[116:119], v[128:131], v[186:189], v[116:119]
	v_mfma_f32_16x16x32_bf16 v[108:111], v[128:131], v[194:197], v[108:111]
	v_mfma_f32_16x16x32_bf16 v[104:107], v[148:151], v[194:197], v[104:107]
	v_mfma_f32_16x16x32_bf16 v[96:99], v[148:151], v[202:205], v[96:99]
	v_mfma_f32_16x16x32_bf16 v[100:103], v[128:131], v[202:205], v[100:103]
	v_mfma_f32_16x16x32_bf16 v[124:127], v[132:135], v[182:185], v[124:127]
	v_mfma_f32_16x16x32_bf16 v[120:123], v[152:155], v[182:185], v[120:123]
	v_mfma_f32_16x16x32_bf16 v[112:115], v[152:155], v[190:193], v[112:115]
	v_mfma_f32_16x16x32_bf16 v[116:119], v[132:135], v[190:193], v[116:119]
	v_mfma_f32_16x16x32_bf16 v[108:111], v[132:135], v[198:201], v[108:111]
	v_mfma_f32_16x16x32_bf16 v[104:107], v[152:155], v[198:201], v[104:107]
	v_mfma_f32_16x16x32_bf16 v[96:99], v[152:155], v[206:209], v[96:99]
	v_mfma_f32_16x16x32_bf16 v[100:103], v[132:135], v[206:209], v[100:103]
	s_setprio 0
	s_setprio 1
	v_mfma_f32_16x16x32_bf16 v[60:63], v[156:159], v[178:181], v[60:63]
	v_mfma_f32_16x16x32_bf16 v[56:59], v[170:173], v[178:181], v[56:59]
	v_mfma_f32_16x16x32_bf16 v[48:51], v[170:173], v[186:189], v[48:51]
	v_mfma_f32_16x16x32_bf16 v[52:55], v[156:159], v[186:189], v[52:55]
	v_mfma_f32_16x16x32_bf16 v[44:47], v[156:159], v[194:197], v[44:47]
	v_mfma_f32_16x16x32_bf16 v[40:43], v[170:173], v[194:197], v[40:43]
	v_mfma_f32_16x16x32_bf16 v[32:35], v[170:173], v[202:205], v[32:35]
	v_mfma_f32_16x16x32_bf16 v[36:39], v[156:159], v[202:205], v[36:39]
	v_mfma_f32_16x16x32_bf16 v[60:63], v[160:163], v[182:185], v[60:63]
	v_mfma_f32_16x16x32_bf16 v[56:59], v[174:177], v[182:185], v[56:59]
	v_mfma_f32_16x16x32_bf16 v[48:51], v[174:177], v[190:193], v[48:51]
	v_mfma_f32_16x16x32_bf16 v[52:55], v[160:163], v[190:193], v[52:55]
	v_mfma_f32_16x16x32_bf16 v[44:47], v[160:163], v[198:201], v[44:47]
	v_mfma_f32_16x16x32_bf16 v[40:43], v[174:177], v[198:201], v[40:43]
	v_mfma_f32_16x16x32_bf16 v[32:35], v[174:177], v[206:209], v[32:35]
	v_mfma_f32_16x16x32_bf16 v[36:39], v[160:163], v[206:209], v[36:39]
	s_setprio 0
	s_barrier
	s_mov_b32 m0, s67
	v_lshl_add_u64 v[210:211], s[30:31], 0, v[140:141]
	s_add_u32 s88, s30, 0x10000
	ds_read_b128 v[178:181], v169 offset:16384
	ds_read_b128 v[182:185], v169 offset:17408
	ds_read_b128 v[186:189], v169 offset:18432
	ds_read_b128 v[190:193], v169 offset:19456
	ds_read_b128 v[194:197], v169 offset:20480
	ds_read_b128 v[198:201], v169 offset:21504
	ds_read_b128 v[202:205], v169 offset:22528
	ds_read_b128 v[206:209], v169 offset:23552
	global_load_lds_dwordx4 v[210:211], off
	v_lshl_add_u64 v[212:213], s[30:31], 0, v[136:137]
	s_mov_b32 m0, s68
	s_addc_u32 s89, s31, 0
	global_load_lds_dwordx4 v[212:213], off
	v_lshl_add_u64 v[214:215], s[88:89], 0, v[140:141]
	s_mov_b32 m0, s69
	v_lshl_add_u64 v[216:217], s[54:55], 0, v[138:139]
	global_load_lds_dwordx4 v[214:215], off
	v_lshl_add_u64 v[214:215], s[88:89], 0, v[136:137]
	s_add_i32 m0, s69, 0x2000
	s_nop 0
	global_load_lds_dwordx4 v[214:215], off
	v_lshl_add_u64 v[214:215], s[54:55], 0, v[142:143]
	s_mov_b32 m0, s25
	s_nop 0
	global_load_lds_dwordx4 v[214:215], off
	s_mov_b32 m0, s58
	s_nop 0
	global_load_lds_dwordx4 v[216:217], off
	s_waitcnt vmcnt(8)
	s_waitcnt lgkmcnt(0)
	s_barrier
; #define PG8_STAGE(bufoff, gbase, voff) do { _Pragma("unroll") for (int _i = 0; _i < 2; ++_i) \
;         __builtin_amdgcn_global_load_lds((const unsigned*)((const char*)(gbase) + (voff)[_i]), (LAS unsigned*)(lds + (bufoff) + ldsw + _i * 8192), 16, 0, 0); } while (0)
; #define PG8_LDA(dst, b, h) do { _Pragma("unroll") for (int m = 0; m < 4; ++m) _Pragma("unroll") for (int k = 0; k < 2; ++k) dst[m][k] = *(const LAS bf16x8*)(lds + PG8_SA(b, h) + aoff + m * 2048 + k * 1024); } while (0)
; #define PG8_LDB(dst, b, h) do { _Pragma("unroll") for (int n = 0; n < 2; ++n) _Pragma("unroll") for (int k = 0; k < 2; ++k) dst[n][k] = *(const LAS bf16x8*)(lds + PG8_SB(b, h) + boff + n * 2048 + k * 1024); } while (0)
; #define PG8_MMA(ai, bj, At, Bt) do { __builtin_amdgcn_s_setprio(1); _Pragma("unroll") for (int m = 0; m < 4; ++m) _Pragma("unroll") for (int n = 0; n < 2; ++n) _Pragma("unroll") for (int k = 0; k < 2; ++k) \
;         acc[ai][bj][m][n] = __builtin_amdgcn_mfma_f32_16x16x32_bf16(Bt[n][k], At[m][k], acc[ai][bj][m][n], 0, 0, 0); __builtin_amdgcn_s_setprio(0); } while (0)
; #define PG8_WAIT_V(n) asm volatile("s_waitcnt vmcnt(" #n ")" ::: "memory")
; #define PG8_WAIT_L(n) asm volatile("s_waitcnt lgkmcnt(" #n ")" ::: "memory")
; #define PG8_BAR __builtin_amdgcn_s_barrier()
; #define PG8_SCHED __builtin_amdgcn_sched_barrier(0)
; template <int FIXED_NT  , class Epi, class Sched>
; __device__ __forceinline__ void gemm_phase(LAS unsigned char* lds, const int tid_in, const int lda, const int ldb, const Sched& S, const Epi& E) {
;     ...
;             PG8_WAIT_V(8); PG8_WAIT_L(0); PG8_BAR; PG8_MMA(1, 0, At, B0); PG8_MMA(1, 1, At, B1); PG8_BAR; PG8_SCHED;
;             PG8_LDB(B0, 1, 0); PG8_LDB(B1, 1, 1); PG8_SCHED; PG8_LDA(At, 1, 0); PG8_STAGE(PG8_SA(0, 1), a2 + hstepA, voffA);
;             PG8_WAIT_V(8); PG8_WAIT_L(0); PG8_BAR; PG8_MMA(0, 0, At, B0); PG8_MMA(0, 1, At, B1); PG8_BAR; PG8_SCHED;
	s_setprio 1
	s_waitcnt lgkmcnt(0)
	v_mfma_f32_16x16x32_bf16 v[92:95], v[128:131], v[178:181], v[92:95]
	v_mfma_f32_16x16x32_bf16 v[88:91], v[148:151], v[178:181], v[88:91]
	v_mfma_f32_16x16x32_bf16 v[80:83], v[148:151], v[186:189], v[80:83]
	v_mfma_f32_16x16x32_bf16 v[84:87], v[128:131], v[186:189], v[84:87]
	v_mfma_f32_16x16x32_bf16 v[76:79], v[128:131], v[194:197], v[76:79]
	v_mfma_f32_16x16x32_bf16 v[72:75], v[148:151], v[194:197], v[72:75]
	v_mfma_f32_16x16x32_bf16 v[64:67], v[148:151], v[202:205], v[64:67]
	v_mfma_f32_16x16x32_bf16 v[68:71], v[128:131], v[202:205], v[68:71]
	v_mfma_f32_16x16x32_bf16 v[92:95], v[132:135], v[182:185], v[92:95]
	v_mfma_f32_16x16x32_bf16 v[88:91], v[152:155], v[182:185], v[88:91]
	v_mfma_f32_16x16x32_bf16 v[80:83], v[152:155], v[190:193], v[80:83]
	v_mfma_f32_16x16x32_bf16 v[84:87], v[132:135], v[190:193], v[84:87]
	v_mfma_f32_16x16x32_bf16 v[76:79], v[132:135], v[198:201], v[76:79]
	v_mfma_f32_16x16x32_bf16 v[72:75], v[152:155], v[198:201], v[72:75]
	v_mfma_f32_16x16x32_bf16 v[64:67], v[152:155], v[206:209], v[64:67]
	v_mfma_f32_16x16x32_bf16 v[68:71], v[132:135], v[206:209], v[68:71]
	s_setprio 0
	s_setprio 1
	v_mfma_f32_16x16x32_bf16 v[28:31], v[156:159], v[178:181], v[28:31]
	v_mfma_f32_16x16x32_bf16 v[24:27], v[170:173], v[178:181], v[24:27]
	v_mfma_f32_16x16x32_bf16 v[16:19], v[170:173], v[186:189], v[16:19]
	v_mfma_f32_16x16x32_bf16 v[20:23], v[156:159], v[186:189], v[20:23]
	v_mfma_f32_16x16x32_bf16 v[12:15], v[156:159], v[194:197], v[12:15]
	v_mfma_f32_16x16x32_bf16 v[8:11], v[170:173], v[194:197], v[8:11]
	v_mfma_f32_16x16x32_bf16 v[0:3], v[170:173], v[202:205], v[0:3]
	v_mfma_f32_16x16x32_bf16 v[4:7], v[156:159], v[202:205], v[4:7]
	v_mfma_f32_16x16x32_bf16 v[28:31], v[160:163], v[182:185], v[28:31]
	v_mfma_f32_16x16x32_bf16 v[24:27], v[174:177], v[182:185], v[24:27]
	v_mfma_f32_16x16x32_bf16 v[16:19], v[174:177], v[190:193], v[16:19]
	v_mfma_f32_16x16x32_bf16 v[20:23], v[160:163], v[190:193], v[20:23]
	v_mfma_f32_16x16x32_bf16 v[12:15], v[160:163], v[198:201], v[12:15]
	v_mfma_f32_16x16x32_bf16 v[8:11], v[174:177], v[198:201], v[8:11]
	v_mfma_f32_16x16x32_bf16 v[0:3], v[174:177], v[206:209], v[0:3]
	v_mfma_f32_16x16x32_bf16 v[4:7], v[160:163], v[206:209], v[4:7]
	s_setprio 0
	s_barrier
	s_add_i32 s74, 0, 0x18000
	s_add_i32 s76, 0, 0x1c000
	v_add_u32_e32 v152, s74, v165
	v_add_u32_e32 v174, s76, v165
	ds_read_b128 v[128:131], v152
	ds_read_b128 v[132:135], v152 offset:1024
	ds_read_b128 v[148:151], v152 offset:2048
	ds_read_b128 v[152:155], v152 offset:3072
	ds_read_b128 v[156:159], v174
	ds_read_b128 v[160:163], v174 offset:1024
	ds_read_b128 v[170:173], v174 offset:2048
	ds_read_b128 v[174:177], v174 offset:3072
	s_add_u32 s54, s54, 0x40000
	s_addc_u32 s55, s55, 0
	s_mov_b32 m0, s59
	v_lshl_add_u64 v[218:219], s[54:55], 0, v[142:143]
	ds_read_b128 v[178:181], v169 offset:32768
	ds_read_b128 v[182:185], v169 offset:33792
	ds_read_b128 v[186:189], v169 offset:34816
	ds_read_b128 v[190:193], v169 offset:35840
	ds_read_b128 v[194:197], v169 offset:36864
	ds_read_b128 v[198:201], v169 offset:37888
	ds_read_b128 v[202:205], v169 offset:38912
	ds_read_b128 v[206:209], v169 offset:39936
	global_load_lds_dwordx4 v[218:219], off
	v_lshl_add_u64 v[218:219], s[54:55], 0, v[138:139]
	s_mov_b32 m0, s60
	s_nop 0
	global_load_lds_dwordx4 v[218:219], off
	s_nop 0
	s_waitcnt vmcnt(8)
	s_waitcnt lgkmcnt(0)
	s_barrier
	s_setprio 1
	s_waitcnt lgkmcnt(0)
	v_mfma_f32_16x16x32_bf16 v[124:127], v[128:131], v[178:181], v[124:127]
	v_mfma_f32_16x16x32_bf16 v[120:123], v[148:151], v[178:181], v[120:123]
	v_mfma_f32_16x16x32_bf16 v[112:115], v[148:151], v[186:189], v[112:115]
	v_mfma_f32_16x16x32_bf16 v[116:119], v[128:131], v[186:189], v[116:119]
	v_mfma_f32_16x16x32_bf16 v[108:111], v[128:131], v[194:197], v[108:111]
	v_mfma_f32_16x16x32_bf16 v[104:107], v[148:151], v[194:197], v[104:107]
	v_mfma_f32_16x16x32_bf16 v[96:99], v[148:151], v[202:205], v[96:99]
	v_mfma_f32_16x16x32_bf16 v[100:103], v[128:131], v[202:205], v[100:103]
	v_mfma_f32_16x16x32_bf16 v[124:127], v[132:135], v[182:185], v[124:127]
	v_mfma_f32_16x16x32_bf16 v[120:123], v[152:155], v[182:185], v[120:123]
	v_mfma_f32_16x16x32_bf16 v[112:115], v[152:155], v[190:193], v[112:115]
	v_mfma_f32_16x16x32_bf16 v[116:119], v[132:135], v[190:193], v[116:119]
	v_mfma_f32_16x16x32_bf16 v[108:111], v[132:135], v[198:201], v[108:111]
	v_mfma_f32_16x16x32_bf16 v[104:107], v[152:155], v[198:201], v[104:107]
	v_mfma_f32_16x16x32_bf16 v[96:99], v[152:155], v[206:209], v[96:99]
	v_mfma_f32_16x16x32_bf16 v[100:103], v[132:135], v[206:209], v[100:103]
	s_setprio 0
	s_setprio 1
	v_mfma_f32_16x16x32_bf16 v[60:63], v[156:159], v[178:181], v[60:63]
	v_mfma_f32_16x16x32_bf16 v[56:59], v[170:173], v[178:181], v[56:59]
	v_mfma_f32_16x16x32_bf16 v[48:51], v[170:173], v[186:189], v[48:51]
	v_mfma_f32_16x16x32_bf16 v[52:55], v[156:159], v[186:189], v[52:55]
	v_mfma_f32_16x16x32_bf16 v[44:47], v[156:159], v[194:197], v[44:47]
	v_mfma_f32_16x16x32_bf16 v[40:43], v[170:173], v[194:197], v[40:43]
	v_mfma_f32_16x16x32_bf16 v[32:35], v[170:173], v[202:205], v[32:35]
	v_mfma_f32_16x16x32_bf16 v[36:39], v[156:159], v[202:205], v[36:39]
	v_mfma_f32_16x16x32_bf16 v[60:63], v[160:163], v[182:185], v[60:63]
	v_mfma_f32_16x16x32_bf16 v[56:59], v[174:177], v[182:185], v[56:59]
	v_mfma_f32_16x16x32_bf16 v[48:51], v[174:177], v[190:193], v[48:51]
	v_mfma_f32_16x16x32_bf16 v[52:55], v[160:163], v[190:193], v[52:55]
	v_mfma_f32_16x16x32_bf16 v[44:47], v[160:163], v[198:201], v[44:47]
	v_mfma_f32_16x16x32_bf16 v[40:43], v[174:177], v[198:201], v[40:43]
	v_mfma_f32_16x16x32_bf16 v[32:35], v[174:177], v[206:209], v[32:35]
	v_mfma_f32_16x16x32_bf16 v[36:39], v[160:163], v[206:209], v[36:39]
	s_setprio 0
	s_barrier
; #define PG8_STAGE(bufoff, gbase, voff) do { _Pragma("unroll") for (int _i = 0; _i < 2; ++_i) \
;         __builtin_amdgcn_global_load_lds((const unsigned*)((const char*)(gbase) + (voff)[_i]), (LAS unsigned*)(lds + (bufoff) + ldsw + _i * 8192), 16, 0, 0); } while (0)
; #define PG8_LDA(dst, b, h) do { _Pragma("unroll") for (int m = 0; m < 4; ++m) _Pragma("unroll") for (int k = 0; k < 2; ++k) dst[m][k] = *(const LAS bf16x8*)(lds + PG8_SA(b, h) + aoff + m * 2048 + k * 1024); } while (0)
; #define PG8_MMA(ai, bj, At, Bt) do { __builtin_amdgcn_s_setprio(1); _Pragma("unroll") for (int m = 0; m < 4; ++m) _Pragma("unroll") for (int n = 0; n < 2; ++n) _Pragma("unroll") for (int k = 0; k < 2; ++k) \
;         acc[ai][bj][m][n] = __builtin_amdgcn_mfma_f32_16x16x32_bf16(Bt[n][k], At[m][k], acc[ai][bj][m][n], 0, 0, 0); __builtin_amdgcn_s_setprio(0); } while (0)
; #define PG8_WAIT_V(n) asm volatile("s_waitcnt vmcnt(" #n ")" ::: "memory")
; #define PG8_WAIT_L(n) asm volatile("s_waitcnt lgkmcnt(" #n ")" ::: "memory")
; #define PG8_BAR __builtin_amdgcn_s_barrier()
; #define PG8_SCHED __builtin_amdgcn_sched_barrier(0)
; template <int FIXED_NT  , class Epi, class Sched>
; __device__ __forceinline__ void gemm_phase(LAS unsigned char* lds, const int tid_in, const int lda, const int ldb, const Sched& S, const Epi& E) {
;     ...
;             PG8_LDA(At, 1, 1); PG8_STAGE(PG8_SB(1, 0), b3, voffB); PG8_STAGE(PG8_SB(1, 1), b3 + hstepB, voffB); PG8_STAGE(PG8_SA(1, 0), a3, voffA);
;             PG8_WAIT_V(8); PG8_WAIT_L(0); PG8_BAR; PG8_MMA(1, 0, At, B0); PG8_MMA(1, 1, At, B1); PG8_BAR; PG8_SCHED;
;         }
	s_add_i32 s54, s74, s45
	v_lshl_add_u64 v[210:211], v[210:211], 0, s[10:11]
	s_mov_b32 m0, s54
	ds_read_b128 v[178:181], v169 offset:49152
	ds_read_b128 v[182:185], v169 offset:50176
	ds_read_b128 v[186:189], v169 offset:51200
	ds_read_b128 v[190:193], v169 offset:52224
	ds_read_b128 v[194:197], v169 offset:53248
	ds_read_b128 v[198:201], v169 offset:54272
	ds_read_b128 v[202:205], v169 offset:55296
	ds_read_b128 v[206:209], v169 offset:56320
	global_load_lds_dwordx4 v[210:211], off
	s_add_i32 m0, s54, 0x2000
	s_add_u32 s30, s30, 0x10080
	v_lshl_add_u64 v[210:211], v[212:213], 0, s[10:11]
	s_addc_u32 s31, s31, 0
	s_add_i32 s54, s76, s45
	global_load_lds_dwordx4 v[210:211], off
	v_lshl_add_u64 v[210:211], s[30:31], 0, v[140:141]
	s_mov_b32 m0, s54
	s_nop 0
	global_load_lds_dwordx4 v[210:211], off
	v_lshl_add_u64 v[210:211], s[30:31], 0, v[136:137]
	s_add_i32 m0, s54, 0x2000
	s_nop 0
	global_load_lds_dwordx4 v[210:211], off
	v_lshl_add_u64 v[210:211], v[214:215], 0, s[10:11]
	s_mov_b32 m0, s62
	s_nop 0
	global_load_lds_dwordx4 v[210:211], off
	v_lshl_add_u64 v[210:211], v[216:217], 0, s[10:11]
	s_mov_b32 m0, s63
	s_nop 0
	global_load_lds_dwordx4 v[210:211], off
	s_waitcnt vmcnt(8)
	s_waitcnt lgkmcnt(0)
	s_barrier
	s_setprio 1
	s_waitcnt lgkmcnt(0)
	v_mfma_f32_16x16x32_bf16 v[92:95], v[128:131], v[178:181], v[92:95]
	v_mfma_f32_16x16x32_bf16 v[88:91], v[148:151], v[178:181], v[88:91]
	v_mfma_f32_16x16x32_bf16 v[80:83], v[148:151], v[186:189], v[80:83]
	v_mfma_f32_16x16x32_bf16 v[84:87], v[128:131], v[186:189], v[84:87]
	v_mfma_f32_16x16x32_bf16 v[76:79], v[128:131], v[194:197], v[76:79]
	v_mfma_f32_16x16x32_bf16 v[72:75], v[148:151], v[194:197], v[72:75]
	v_mfma_f32_16x16x32_bf16 v[64:67], v[148:151], v[202:205], v[64:67]
	v_mfma_f32_16x16x32_bf16 v[68:71], v[128:131], v[202:205], v[68:71]
	v_mfma_f32_16x16x32_bf16 v[92:95], v[132:135], v[182:185], v[92:95]
	v_mfma_f32_16x16x32_bf16 v[88:91], v[152:155], v[182:185], v[88:91]
	v_mfma_f32_16x16x32_bf16 v[80:83], v[152:155], v[190:193], v[80:83]
	v_mfma_f32_16x16x32_bf16 v[84:87], v[132:135], v[190:193], v[84:87]
	v_mfma_f32_16x16x32_bf16 v[76:79], v[132:135], v[198:201], v[76:79]
	v_mfma_f32_16x16x32_bf16 v[72:75], v[152:155], v[198:201], v[72:75]
	v_mfma_f32_16x16x32_bf16 v[64:67], v[152:155], v[206:209], v[64:67]
	v_mfma_f32_16x16x32_bf16 v[68:71], v[132:135], v[206:209], v[68:71]
	s_setprio 0
	s_setprio 1
	v_mfma_f32_16x16x32_bf16 v[28:31], v[156:159], v[178:181], v[28:31]
	v_mfma_f32_16x16x32_bf16 v[24:27], v[170:173], v[178:181], v[24:27]
	v_mfma_f32_16x16x32_bf16 v[16:19], v[170:173], v[186:189], v[16:19]
	v_mfma_f32_16x16x32_bf16 v[20:23], v[156:159], v[186:189], v[20:23]
	v_mfma_f32_16x16x32_bf16 v[12:15], v[156:159], v[194:197], v[12:15]
	v_mfma_f32_16x16x32_bf16 v[8:11], v[170:173], v[194:197], v[8:11]
	v_mfma_f32_16x16x32_bf16 v[0:3], v[170:173], v[202:205], v[0:3]
	v_mfma_f32_16x16x32_bf16 v[4:7], v[156:159], v[202:205], v[4:7]
	v_mfma_f32_16x16x32_bf16 v[28:31], v[160:163], v[182:185], v[28:31]
	v_mfma_f32_16x16x32_bf16 v[24:27], v[174:177], v[182:185], v[24:27]
	v_mfma_f32_16x16x32_bf16 v[16:19], v[174:177], v[190:193], v[16:19]
	v_mfma_f32_16x16x32_bf16 v[20:23], v[160:163], v[190:193], v[20:23]
	v_mfma_f32_16x16x32_bf16 v[12:15], v[160:163], v[198:201], v[12:15]
	v_mfma_f32_16x16x32_bf16 v[8:11], v[174:177], v[198:201], v[8:11]
	v_mfma_f32_16x16x32_bf16 v[0:3], v[174:177], v[206:209], v[0:3]
	v_mfma_f32_16x16x32_bf16 v[4:7], v[160:163], v[206:209], v[4:7]
	s_setprio 0
	s_barrier
	s_add_u32 s28, s28, 0x100
	s_addc_u32 s29, s29, 0
	s_add_u32 s17, s17, 0x100
	s_addc_u32 s72, s72, 0
	s_cmp_ge_i32 s73, s33
	s_mov_b32 s30, s73
	s_cbranch_scc0 .LBB0_598
	s_and_b64 vcc, exec, s[14:15]
	s_cbranch_vccz .LBB0_601

; #define PG8_STAGE(bufoff, gbase, voff) do { _Pragma("unroll") for (int _i = 0; _i < 2; ++_i) \
;         __builtin_amdgcn_global_load_lds((const unsigned*)((const char*)(gbase) + (voff)[_i]), (LAS unsigned*)(lds + (bufoff) + ldsw + _i * 8192), 16, 0, 0); } while (0)
; #define PG8_LDA(dst, b, h) do { _Pragma("unroll") for (int m = 0; m < 4; ++m) _Pragma("unroll") for (int k = 0; k < 2; ++k) dst[m][k] = *(const LAS bf16x8*)(lds + PG8_SA(b, h) + aoff + m * 2048 + k * 1024); } while (0)
; #define PG8_LDB(dst, b, h) do { _Pragma("unroll") for (int n = 0; n < 2; ++n) _Pragma("unroll") for (int k = 0; k < 2; ++k) dst[n][k] = *(const LAS bf16x8*)(lds + PG8_SB(b, h) + boff + n * 2048 + k * 1024); } while (0)
; #define PG8_MMA(ai, bj, At, Bt) do { __builtin_amdgcn_s_setprio(1); _Pragma("unroll") for (int m = 0; m < 4; ++m) _Pragma("unroll") for (int n = 0; n < 2; ++n) _Pragma("unroll") for (int k = 0; k < 2; ++k) \
;         acc[ai][bj][m][n] = __builtin_amdgcn_mfma_f32_16x16x32_bf16(Bt[n][k], At[m][k], acc[ai][bj][m][n], 0, 0, 0); __builtin_amdgcn_s_setprio(0); } while (0)
; #define PG8_WAIT_V(n) asm volatile("s_waitcnt vmcnt(" #n ")" ::: "memory")
; #define PG8_WAIT_L(n) asm volatile("s_waitcnt lgkmcnt(" #n ")" ::: "memory")
; #define PG8_BAR __builtin_amdgcn_s_barrier()
; #define PG8_SCHED __builtin_amdgcn_sched_barrier(0)
; template <int FIXED_NT  , class Epi, class Sched>
; __device__ __forceinline__ void gemm_phase(LAS unsigned char* lds, const int tid_in, const int lda, const int ldb, const Sched& S, const Epi& E) {
;     ...
;         for (int t = 0; t < nt; t += 2) {
;             const bool last = (t == nt - 2);
;             const char* a1 = cA + (size_t)(t + 1) * kstep;
;             const char* a2 = last ? nA : cA + (size_t)(t + 2) * kstep; const char* b2 = last ? nB : cB + (size_t)(t + 2) * kstep;
;             const char* a3 = a2 + kstep; const char* b3 = b2 + kstep;
;             PG8_LDB(B0, 0, 0); PG8_LDB(B1, 0, 1); PG8_SCHED; PG8_LDA(At, 0, 0); PG8_STAGE(PG8_SA(1, 1), a1 + hstepA, voffA);
;             PG8_WAIT_V(8); PG8_WAIT_L(0); PG8_BAR; PG8_MMA(0, 0, At, B0); PG8_MMA(0, 1, At, B1); PG8_BAR; PG8_SCHED;
;             PG8_LDA(At, 0, 1); PG8_STAGE(PG8_SB(0, 0), b2, voffB); PG8_STAGE(PG8_SB(0, 1), b2 + hstepB, voffB); PG8_STAGE(PG8_SA(0, 0), a2, voffA);
.LBB0_689:
	v_add_u32_e32 v1, s35, v226
	ds_read_b128 v[132:135], v1
	ds_read_b128 v[136:139], v1 offset:1024
	ds_read_b128 v[140:143], v1 offset:2048
	ds_read_b128 v[144:147], v1 offset:3072
	v_add_u32_e32 v1, s44, v226
	ds_read_b128 v[148:151], v1
	ds_read_b128 v[152:155], v1 offset:1024
	ds_read_b128 v[156:159], v1 offset:2048
	ds_read_b128 v[160:163], v1 offset:3072
	s_add_i32 s68, s62, 2
	s_add_u32 s63, s60, 0xfffc0080
	s_addc_u32 s64, s61, -1
	s_cmp_eq_u32 s33, s62
	s_cselect_b32 s62, s31, s66
	s_cselect_b32 s65, s9, s64
	s_cselect_b32 s64, s14, s63
	s_cselect_b32 s63, s29, s67
	v_lshl_add_u64 v[2:3], s[60:61], 0, v[208:209]
	s_add_i32 m0, s70, 0xc000
	ds_read_b128 v[164:167], v231
	ds_read_b128 v[168:171], v231 offset:1024
	ds_read_b128 v[172:175], v231 offset:2048
	ds_read_b128 v[176:179], v231 offset:3072
	ds_read_b128 v[180:183], v231 offset:4096
	ds_read_b128 v[184:187], v231 offset:5120
	ds_read_b128 v[188:191], v231 offset:6144
	ds_read_b128 v[192:195], v231 offset:7168
	global_load_lds_dwordx4 v[2:3], off
	v_lshl_add_u64 v[2:3], s[60:61], 0, v[210:211]
	s_add_i32 m0, s70, 0xe000
	s_nop 0
	global_load_lds_dwordx4 v[2:3], off
	s_nop 0
	s_waitcnt vmcnt(8)
	s_waitcnt lgkmcnt(0)
	s_barrier
	s_setprio 1
	s_waitcnt lgkmcnt(0)
	v_mfma_f32_16x16x32_bf16 v[120:123], v[132:135], v[164:167], v[120:123]
	v_mfma_f32_16x16x32_bf16 v[128:131], v[140:143], v[164:167], v[128:131]
	v_mfma_f32_16x16x32_bf16 v[124:127], v[140:143], v[172:175], v[124:127]
	v_mfma_f32_16x16x32_bf16 v[112:115], v[132:135], v[172:175], v[112:115]
	v_mfma_f32_16x16x32_bf16 v[104:107], v[132:135], v[180:183], v[104:107]
	v_mfma_f32_16x16x32_bf16 v[116:119], v[140:143], v[180:183], v[116:119]
	v_mfma_f32_16x16x32_bf16 v[108:111], v[140:143], v[188:191], v[108:111]
	v_mfma_f32_16x16x32_bf16 v[96:99], v[132:135], v[188:191], v[96:99]
	v_mfma_f32_16x16x32_bf16 v[120:123], v[136:139], v[168:171], v[120:123]
	v_mfma_f32_16x16x32_bf16 v[128:131], v[144:147], v[168:171], v[128:131]
	v_mfma_f32_16x16x32_bf16 v[124:127], v[144:147], v[176:179], v[124:127]
	v_mfma_f32_16x16x32_bf16 v[112:115], v[136:139], v[176:179], v[112:115]
	v_mfma_f32_16x16x32_bf16 v[104:107], v[136:139], v[184:187], v[104:107]
	v_mfma_f32_16x16x32_bf16 v[116:119], v[144:147], v[184:187], v[116:119]
	v_mfma_f32_16x16x32_bf16 v[108:111], v[144:147], v[192:195], v[108:111]
	v_mfma_f32_16x16x32_bf16 v[96:99], v[136:139], v[192:195], v[96:99]
	s_setprio 0
	s_setprio 1
	v_mfma_f32_16x16x32_bf16 v[88:91], v[148:151], v[164:167], v[88:91]
	v_mfma_f32_16x16x32_bf16 v[100:103], v[156:159], v[164:167], v[100:103]
	v_mfma_f32_16x16x32_bf16 v[92:95], v[156:159], v[172:175], v[92:95]
	v_mfma_f32_16x16x32_bf16 v[80:83], v[148:151], v[172:175], v[80:83]
	v_mfma_f32_16x16x32_bf16 v[72:75], v[148:151], v[180:183], v[72:75]
	v_mfma_f32_16x16x32_bf16 v[84:87], v[156:159], v[180:183], v[84:87]
	v_mfma_f32_16x16x32_bf16 v[76:79], v[156:159], v[188:191], v[76:79]
	v_mfma_f32_16x16x32_bf16 v[64:67], v[148:151], v[188:191], v[64:67]
	v_mfma_f32_16x16x32_bf16 v[88:91], v[152:155], v[168:171], v[88:91]
	v_mfma_f32_16x16x32_bf16 v[100:103], v[160:163], v[168:171], v[100:103]
	v_mfma_f32_16x16x32_bf16 v[92:95], v[160:163], v[176:179], v[92:95]
	v_mfma_f32_16x16x32_bf16 v[80:83], v[152:155], v[176:179], v[80:83]
	v_mfma_f32_16x16x32_bf16 v[72:75], v[152:155], v[184:187], v[72:75]
	v_mfma_f32_16x16x32_bf16 v[84:87], v[160:163], v[184:187], v[84:87]
	v_mfma_f32_16x16x32_bf16 v[76:79], v[160:163], v[192:195], v[76:79]
	v_mfma_f32_16x16x32_bf16 v[64:67], v[152:155], v[192:195], v[64:67]
	s_setprio 0
	s_barrier
	s_add_i32 s69, s35, s45
	v_lshl_add_u64 v[196:197], s[62:63], 0, v[202:203]
	s_mov_b32 m0, s69
	ds_read_b128 v[164:167], v231 offset:16384
	ds_read_b128 v[168:171], v231 offset:17408
	ds_read_b128 v[172:175], v231 offset:18432
	ds_read_b128 v[176:179], v231 offset:19456
	ds_read_b128 v[180:183], v231 offset:20480
	ds_read_b128 v[184:187], v231 offset:21504
	ds_read_b128 v[188:191], v231 offset:22528
	ds_read_b128 v[192:195], v231 offset:23552
	global_load_lds_dwordx4 v[196:197], off
	s_add_i32 m0, s69, 0x2000
	s_add_u32 s92, s62, 0x40000
	v_lshl_add_u64 v[198:199], s[62:63], 0, v[206:207]
	s_addc_u32 s93, s63, 0
	s_add_i32 s69, s44, s45
	global_load_lds_dwordx4 v[198:199], off
	v_lshl_add_u64 v[2:3], s[92:93], 0, v[202:203]
	s_mov_b32 m0, s69
	v_lshl_add_u64 v[212:213], s[64:65], 0, v[200:201]
	global_load_lds_dwordx4 v[2:3], off
	v_lshl_add_u64 v[2:3], s[92:93], 0, v[206:207]
	s_add_i32 m0, s69, 0x2000
	v_lshl_add_u64 v[214:215], s[64:65], 0, v[204:205]
	global_load_lds_dwordx4 v[2:3], off
	s_mov_b32 m0, s70
	s_nop 0
	global_load_lds_dwordx4 v[212:213], off
	s_mov_b32 m0, s71
	s_nop 0
	global_load_lds_dwordx4 v[214:215], off
	s_waitcnt vmcnt(8)
	s_waitcnt lgkmcnt(0)
	s_barrier
; #define PG8_STAGE(bufoff, gbase, voff) do { _Pragma("unroll") for (int _i = 0; _i < 2; ++_i) \
;         __builtin_amdgcn_global_load_lds((const unsigned*)((const char*)(gbase) + (voff)[_i]), (LAS unsigned*)(lds + (bufoff) + ldsw + _i * 8192), 16, 0, 0); } while (0)
; #define PG8_LDA(dst, b, h) do { _Pragma("unroll") for (int m = 0; m < 4; ++m) _Pragma("unroll") for (int k = 0; k < 2; ++k) dst[m][k] = *(const LAS bf16x8*)(lds + PG8_SA(b, h) + aoff + m * 2048 + k * 1024); } while (0)
; #define PG8_LDB(dst, b, h) do { _Pragma("unroll") for (int n = 0; n < 2; ++n) _Pragma("unroll") for (int k = 0; k < 2; ++k) dst[n][k] = *(const LAS bf16x8*)(lds + PG8_SB(b, h) + boff + n * 2048 + k * 1024); } while (0)
; #define PG8_MMA(ai, bj, At, Bt) do { __builtin_amdgcn_s_setprio(1); _Pragma("unroll") for (int m = 0; m < 4; ++m) _Pragma("unroll") for (int n = 0; n < 2; ++n) _Pragma("unroll") for (int k = 0; k < 2; ++k) \
;         acc[ai][bj][m][n] = __builtin_amdgcn_mfma_f32_16x16x32_bf16(Bt[n][k], At[m][k], acc[ai][bj][m][n], 0, 0, 0); __builtin_amdgcn_s_setprio(0); } while (0)
; #define PG8_WAIT_V(n) asm volatile("s_waitcnt vmcnt(" #n ")" ::: "memory")
; #define PG8_WAIT_L(n) asm volatile("s_waitcnt lgkmcnt(" #n ")" ::: "memory")
; #define PG8_BAR __builtin_amdgcn_s_barrier()
; #define PG8_SCHED __builtin_amdgcn_sched_barrier(0)
; template <int FIXED_NT  , class Epi, class Sched>
; __device__ __forceinline__ void gemm_phase(LAS unsigned char* lds, const int tid_in, const int lda, const int ldb, const Sched& S, const Epi& E) {
;     ...
;             PG8_WAIT_V(8); PG8_WAIT_L(0); PG8_BAR; PG8_MMA(1, 0, At, B0); PG8_MMA(1, 1, At, B1); PG8_BAR; PG8_SCHED;
;             PG8_LDB(B0, 1, 0); PG8_LDB(B1, 1, 1); PG8_SCHED; PG8_LDA(At, 1, 0); PG8_STAGE(PG8_SA(0, 1), a2 + hstepA, voffA);
;             PG8_WAIT_V(8); PG8_WAIT_L(0); PG8_BAR; PG8_MMA(0, 0, At, B0); PG8_MMA(0, 1, At, B1); PG8_BAR; PG8_SCHED;
	s_setprio 1
	s_waitcnt lgkmcnt(0)
	v_mfma_f32_16x16x32_bf16 v[56:59], v[132:135], v[164:167], v[56:59]
	v_mfma_f32_16x16x32_bf16 v[68:71], v[140:143], v[164:167], v[68:71]
	v_mfma_f32_16x16x32_bf16 v[60:63], v[140:143], v[172:175], v[60:63]
	v_mfma_f32_16x16x32_bf16 v[48:51], v[132:135], v[172:175], v[48:51]
	v_mfma_f32_16x16x32_bf16 v[40:43], v[132:135], v[180:183], v[40:43]
	v_mfma_f32_16x16x32_bf16 v[52:55], v[140:143], v[180:183], v[52:55]
	v_mfma_f32_16x16x32_bf16 v[44:47], v[140:143], v[188:191], v[44:47]
	v_mfma_f32_16x16x32_bf16 v[32:35], v[132:135], v[188:191], v[32:35]
	v_mfma_f32_16x16x32_bf16 v[56:59], v[136:139], v[168:171], v[56:59]
	v_mfma_f32_16x16x32_bf16 v[68:71], v[144:147], v[168:171], v[68:71]
	v_mfma_f32_16x16x32_bf16 v[60:63], v[144:147], v[176:179], v[60:63]
	v_mfma_f32_16x16x32_bf16 v[48:51], v[136:139], v[176:179], v[48:51]
	v_mfma_f32_16x16x32_bf16 v[40:43], v[136:139], v[184:187], v[40:43]
	v_mfma_f32_16x16x32_bf16 v[52:55], v[144:147], v[184:187], v[52:55]
	v_mfma_f32_16x16x32_bf16 v[44:47], v[144:147], v[192:195], v[44:47]
	v_mfma_f32_16x16x32_bf16 v[32:35], v[136:139], v[192:195], v[32:35]
	s_setprio 0
	s_setprio 1
	v_mfma_f32_16x16x32_bf16 v[24:27], v[148:151], v[164:167], v[24:27]
	v_mfma_f32_16x16x32_bf16 v[36:39], v[156:159], v[164:167], v[36:39]
	v_mfma_f32_16x16x32_bf16 v[28:31], v[156:159], v[172:175], v[28:31]
	v_mfma_f32_16x16x32_bf16 v[16:19], v[148:151], v[172:175], v[16:19]
	v_mfma_f32_16x16x32_bf16 v[8:11], v[148:151], v[180:183], v[8:11]
	v_mfma_f32_16x16x32_bf16 v[20:23], v[156:159], v[180:183], v[20:23]
	v_mfma_f32_16x16x32_bf16 v[12:15], v[156:159], v[188:191], v[12:15]
	v_mfma_f32_16x16x32_bf16 v[2:5], v[148:151], v[188:191], v[4:7]
	v_mfma_f32_16x16x32_bf16 v[24:27], v[152:155], v[168:171], v[24:27]
	v_mfma_f32_16x16x32_bf16 v[36:39], v[160:163], v[168:171], v[36:39]
	v_mfma_f32_16x16x32_bf16 v[28:31], v[160:163], v[176:179], v[28:31]
	v_mfma_f32_16x16x32_bf16 v[16:19], v[152:155], v[176:179], v[16:19]
	v_mfma_f32_16x16x32_bf16 v[8:11], v[152:155], v[184:187], v[8:11]
	v_mfma_f32_16x16x32_bf16 v[20:23], v[160:163], v[184:187], v[20:23]
	v_mfma_f32_16x16x32_bf16 v[12:15], v[160:163], v[192:195], v[12:15]
	v_mfma_f32_16x16x32_bf16 v[2:5], v[152:155], v[192:195], v[2:5]
	s_setprio 0
	s_barrier
	s_add_i32 s69, 0, 0x18000
	v_add_u32_e32 v1, s69, v226
	s_add_i32 s79, 0, 0x1c000
	ds_read_b128 v[132:135], v1
	ds_read_b128 v[136:139], v1 offset:1024
	ds_read_b128 v[140:143], v1 offset:2048
	ds_read_b128 v[144:147], v1 offset:3072
	v_add_u32_e32 v1, s79, v226
	ds_read_b128 v[148:151], v1
	ds_read_b128 v[152:155], v1 offset:1024
	ds_read_b128 v[156:159], v1 offset:2048
	ds_read_b128 v[160:163], v1 offset:3072
	s_add_u32 s64, s64, 0x40000
	s_addc_u32 s65, s65, 0
	s_mov_b32 m0, s72
	v_lshl_add_u64 v[6:7], s[64:65], 0, v[200:201]
	ds_read_b128 v[164:167], v231 offset:32768
	ds_read_b128 v[168:171], v231 offset:33792
	ds_read_b128 v[172:175], v231 offset:34816
	ds_read_b128 v[176:179], v231 offset:35840
	ds_read_b128 v[180:183], v231 offset:36864
	ds_read_b128 v[184:187], v231 offset:37888
	ds_read_b128 v[188:191], v231 offset:38912
	ds_read_b128 v[192:195], v231 offset:39936
	global_load_lds_dwordx4 v[6:7], off
	v_lshl_add_u64 v[6:7], s[64:65], 0, v[204:205]
	s_mov_b32 m0, s73
	s_nop 0
	global_load_lds_dwordx4 v[6:7], off
	s_nop 0
	s_waitcnt vmcnt(8)
	s_waitcnt lgkmcnt(0)
	s_barrier
	s_setprio 1
	s_waitcnt lgkmcnt(0)
	v_mfma_f32_16x16x32_bf16 v[120:123], v[132:135], v[164:167], v[120:123]
	v_mfma_f32_16x16x32_bf16 v[128:131], v[140:143], v[164:167], v[128:131]
	v_mfma_f32_16x16x32_bf16 v[124:127], v[140:143], v[172:175], v[124:127]
	v_mfma_f32_16x16x32_bf16 v[112:115], v[132:135], v[172:175], v[112:115]
	v_mfma_f32_16x16x32_bf16 v[104:107], v[132:135], v[180:183], v[104:107]
	v_mfma_f32_16x16x32_bf16 v[116:119], v[140:143], v[180:183], v[116:119]
	v_mfma_f32_16x16x32_bf16 v[108:111], v[140:143], v[188:191], v[108:111]
	v_mfma_f32_16x16x32_bf16 v[96:99], v[132:135], v[188:191], v[96:99]
	v_mfma_f32_16x16x32_bf16 v[120:123], v[136:139], v[168:171], v[120:123]
	v_mfma_f32_16x16x32_bf16 v[128:131], v[144:147], v[168:171], v[128:131]
	v_mfma_f32_16x16x32_bf16 v[124:127], v[144:147], v[176:179], v[124:127]
	v_mfma_f32_16x16x32_bf16 v[112:115], v[136:139], v[176:179], v[112:115]
	v_mfma_f32_16x16x32_bf16 v[104:107], v[136:139], v[184:187], v[104:107]
	v_mfma_f32_16x16x32_bf16 v[116:119], v[144:147], v[184:187], v[116:119]
	v_mfma_f32_16x16x32_bf16 v[108:111], v[144:147], v[192:195], v[108:111]
	v_mfma_f32_16x16x32_bf16 v[96:99], v[136:139], v[192:195], v[96:99]
	s_setprio 0
	s_setprio 1
	v_mfma_f32_16x16x32_bf16 v[88:91], v[148:151], v[164:167], v[88:91]
	v_mfma_f32_16x16x32_bf16 v[100:103], v[156:159], v[164:167], v[100:103]
	v_mfma_f32_16x16x32_bf16 v[92:95], v[156:159], v[172:175], v[92:95]
	v_mfma_f32_16x16x32_bf16 v[80:83], v[148:151], v[172:175], v[80:83]
	v_mfma_f32_16x16x32_bf16 v[72:75], v[148:151], v[180:183], v[72:75]
	v_mfma_f32_16x16x32_bf16 v[84:87], v[156:159], v[180:183], v[84:87]
	v_mfma_f32_16x16x32_bf16 v[76:79], v[156:159], v[188:191], v[76:79]
	v_mfma_f32_16x16x32_bf16 v[64:67], v[148:151], v[188:191], v[64:67]
	v_mfma_f32_16x16x32_bf16 v[88:91], v[152:155], v[168:171], v[88:91]
	v_mfma_f32_16x16x32_bf16 v[100:103], v[160:163], v[168:171], v[100:103]
	v_mfma_f32_16x16x32_bf16 v[92:95], v[160:163], v[176:179], v[92:95]
	v_mfma_f32_16x16x32_bf16 v[80:83], v[152:155], v[176:179], v[80:83]
	v_mfma_f32_16x16x32_bf16 v[72:75], v[152:155], v[184:187], v[72:75]
	v_mfma_f32_16x16x32_bf16 v[84:87], v[160:163], v[184:187], v[84:87]
	v_mfma_f32_16x16x32_bf16 v[76:79], v[160:163], v[192:195], v[76:79]
	v_mfma_f32_16x16x32_bf16 v[64:67], v[152:155], v[192:195], v[64:67]
	s_setprio 0
	s_barrier
; #define PG8_STAGE(bufoff, gbase, voff) do { _Pragma("unroll") for (int _i = 0; _i < 2; ++_i) \
;         __builtin_amdgcn_global_load_lds((const unsigned*)((const char*)(gbase) + (voff)[_i]), (LAS unsigned*)(lds + (bufoff) + ldsw + _i * 8192), 16, 0, 0); } while (0)
; #define PG8_LDA(dst, b, h) do { _Pragma("unroll") for (int m = 0; m < 4; ++m) _Pragma("unroll") for (int k = 0; k < 2; ++k) dst[m][k] = *(const LAS bf16x8*)(lds + PG8_SA(b, h) + aoff + m * 2048 + k * 1024); } while (0)
; #define PG8_MMA(ai, bj, At, Bt) do { __builtin_amdgcn_s_setprio(1); _Pragma("unroll") for (int m = 0; m < 4; ++m) _Pragma("unroll") for (int n = 0; n < 2; ++n) _Pragma("unroll") for (int k = 0; k < 2; ++k) \
;         acc[ai][bj][m][n] = __builtin_amdgcn_mfma_f32_16x16x32_bf16(Bt[n][k], At[m][k], acc[ai][bj][m][n], 0, 0, 0); __builtin_amdgcn_s_setprio(0); } while (0)
; #define PG8_WAIT_V(n) asm volatile("s_waitcnt vmcnt(" #n ")" ::: "memory")
; #define PG8_WAIT_L(n) asm volatile("s_waitcnt lgkmcnt(" #n ")" ::: "memory")
; #define PG8_BAR __builtin_amdgcn_s_barrier()
; #define PG8_SCHED __builtin_amdgcn_sched_barrier(0)
; template <int FIXED_NT  , class Epi, class Sched>
; __device__ __forceinline__ void gemm_phase(LAS unsigned char* lds, const int tid_in, const int lda, const int ldb, const Sched& S, const Epi& E) {
;     ...
;             PG8_LDA(At, 1, 1); PG8_STAGE(PG8_SB(1, 0), b3, voffB); PG8_STAGE(PG8_SB(1, 1), b3 + hstepB, voffB); PG8_STAGE(PG8_SA(1, 0), a3, voffA);
;             PG8_WAIT_V(8); PG8_WAIT_L(0); PG8_BAR; PG8_MMA(1, 0, At, B0); PG8_MMA(1, 1, At, B1); PG8_BAR; PG8_SCHED;
;         }
	s_add_i32 s64, s69, s45
	v_lshl_add_u64 v[6:7], v[196:197], 0, s[18:19]
	s_mov_b32 m0, s64
	ds_read_b128 v[164:167], v231 offset:49152
	ds_read_b128 v[168:171], v231 offset:50176
	ds_read_b128 v[172:175], v231 offset:51200
	ds_read_b128 v[176:179], v231 offset:52224
	ds_read_b128 v[180:183], v231 offset:53248
	ds_read_b128 v[184:187], v231 offset:54272
	ds_read_b128 v[188:191], v231 offset:55296
	ds_read_b128 v[192:195], v231 offset:56320
	global_load_lds_dwordx4 v[6:7], off
	s_add_i32 m0, s64, 0x2000
	s_add_u32 s62, s62, 0x40080
	v_lshl_add_u64 v[6:7], v[198:199], 0, s[18:19]
	s_addc_u32 s63, s63, 0
	s_add_i32 s64, s79, s45
	global_load_lds_dwordx4 v[6:7], off
	v_lshl_add_u64 v[6:7], s[62:63], 0, v[202:203]
	s_mov_b32 m0, s64
	s_nop 0
	global_load_lds_dwordx4 v[6:7], off
	v_lshl_add_u64 v[6:7], s[62:63], 0, v[206:207]
	s_add_i32 m0, s64, 0x2000
	s_nop 0
	global_load_lds_dwordx4 v[6:7], off
	v_lshl_add_u64 v[6:7], v[212:213], 0, s[18:19]
	s_mov_b32 m0, s76
	s_nop 0
	global_load_lds_dwordx4 v[6:7], off
	v_lshl_add_u64 v[6:7], v[214:215], 0, s[18:19]
	s_mov_b32 m0, s85
	s_nop 0
	global_load_lds_dwordx4 v[6:7], off
	s_waitcnt vmcnt(8)
	s_waitcnt lgkmcnt(0)
	s_barrier
	s_setprio 1
	s_waitcnt lgkmcnt(0)
	v_mfma_f32_16x16x32_bf16 v[56:59], v[132:135], v[164:167], v[56:59]
	v_mfma_f32_16x16x32_bf16 v[68:71], v[140:143], v[164:167], v[68:71]
	v_mfma_f32_16x16x32_bf16 v[60:63], v[140:143], v[172:175], v[60:63]
	v_mfma_f32_16x16x32_bf16 v[48:51], v[132:135], v[172:175], v[48:51]
	v_mfma_f32_16x16x32_bf16 v[40:43], v[132:135], v[180:183], v[40:43]
	v_mfma_f32_16x16x32_bf16 v[52:55], v[140:143], v[180:183], v[52:55]
	v_mfma_f32_16x16x32_bf16 v[44:47], v[140:143], v[188:191], v[44:47]
	v_mfma_f32_16x16x32_bf16 v[32:35], v[132:135], v[188:191], v[32:35]
	v_mfma_f32_16x16x32_bf16 v[56:59], v[136:139], v[168:171], v[56:59]
	v_mfma_f32_16x16x32_bf16 v[68:71], v[144:147], v[168:171], v[68:71]
	v_mfma_f32_16x16x32_bf16 v[60:63], v[144:147], v[176:179], v[60:63]
	v_mfma_f32_16x16x32_bf16 v[48:51], v[136:139], v[176:179], v[48:51]
	v_mfma_f32_16x16x32_bf16 v[40:43], v[136:139], v[184:187], v[40:43]
	v_mfma_f32_16x16x32_bf16 v[52:55], v[144:147], v[184:187], v[52:55]
	v_mfma_f32_16x16x32_bf16 v[44:47], v[144:147], v[192:195], v[44:47]
	v_mfma_f32_16x16x32_bf16 v[32:35], v[136:139], v[192:195], v[32:35]
	s_setprio 0
	s_setprio 1
	v_mfma_f32_16x16x32_bf16 v[24:27], v[148:151], v[164:167], v[24:27]
	v_mfma_f32_16x16x32_bf16 v[36:39], v[156:159], v[164:167], v[36:39]
	v_mfma_f32_16x16x32_bf16 v[28:31], v[156:159], v[172:175], v[28:31]
	v_mfma_f32_16x16x32_bf16 v[16:19], v[148:151], v[172:175], v[16:19]
	v_mfma_f32_16x16x32_bf16 v[6:9], v[148:151], v[180:183], v[8:11]
	v_mfma_f32_16x16x32_bf16 v[20:23], v[156:159], v[180:183], v[20:23]
	v_mfma_f32_16x16x32_bf16 v[12:15], v[156:159], v[188:191], v[12:15]
	v_mfma_f32_16x16x32_bf16 v[2:5], v[148:151], v[188:191], v[2:5]
	v_mfma_f32_16x16x32_bf16 v[24:27], v[152:155], v[168:171], v[24:27]
	v_mfma_f32_16x16x32_bf16 v[36:39], v[160:163], v[168:171], v[36:39]
	v_mfma_f32_16x16x32_bf16 v[28:31], v[160:163], v[176:179], v[28:31]
	v_mfma_f32_16x16x32_bf16 v[16:19], v[152:155], v[176:179], v[16:19]
	v_mfma_f32_16x16x32_bf16 v[8:11], v[152:155], v[184:187], v[6:9]
	v_mfma_f32_16x16x32_bf16 v[20:23], v[160:163], v[184:187], v[20:23]
	v_mfma_f32_16x16x32_bf16 v[12:15], v[160:163], v[192:195], v[12:15]
	v_mfma_f32_16x16x32_bf16 v[4:7], v[152:155], v[192:195], v[2:5]
	s_setprio 0
	s_barrier
	s_add_u32 s60, s60, 0x100
	s_addc_u32 s61, s61, 0
	s_add_u32 s66, s66, 0x100
	s_addc_u32 s67, s67, 0
	s_cmp_ge_i32 s68, s7
	s_mov_b32 s62, s68
	s_cbranch_scc0 .LBB0_689

; #define PG8_STAGE(bufoff, gbase, voff) do { _Pragma("unroll") for (int _i = 0; _i < 2; ++_i) \
;         __builtin_amdgcn_global_load_lds((const unsigned*)((const char*)(gbase) + (voff)[_i]), (LAS unsigned*)(lds + (bufoff) + ldsw + _i * 8192), 16, 0, 0); } while (0)
; #define PG8_LDA(dst, b, h) do { _Pragma("unroll") for (int m = 0; m < 4; ++m) _Pragma("unroll") for (int k = 0; k < 2; ++k) dst[m][k] = *(const LAS bf16x8*)(lds + PG8_SA(b, h) + aoff + m * 2048 + k * 1024); } while (0)
; #define PG8_LDB(dst, b, h) do { _Pragma("unroll") for (int n = 0; n < 2; ++n) _Pragma("unroll") for (int k = 0; k < 2; ++k) dst[n][k] = *(const LAS bf16x8*)(lds + PG8_SB(b, h) + boff + n * 2048 + k * 1024); } while (0)
; #define PG8_MMA(ai, bj, At, Bt) do { __builtin_amdgcn_s_setprio(1); _Pragma("unroll") for (int m = 0; m < 4; ++m) _Pragma("unroll") for (int n = 0; n < 2; ++n) _Pragma("unroll") for (int k = 0; k < 2; ++k) \
;         acc[ai][bj][m][n] = __builtin_amdgcn_mfma_f32_16x16x32_bf16(Bt[n][k], At[m][k], acc[ai][bj][m][n], 0, 0, 0); __builtin_amdgcn_s_setprio(0); } while (0)
; #define PG8_WAIT_V(n) asm volatile("s_waitcnt vmcnt(" #n ")" ::: "memory")
; #define PG8_WAIT_L(n) asm volatile("s_waitcnt lgkmcnt(" #n ")" ::: "memory")
; #define PG8_BAR __builtin_amdgcn_s_barrier()
; #define PG8_SCHED __builtin_amdgcn_sched_barrier(0)
; template <int FIXED_NT  , class Epi, class Sched>
; __device__ __forceinline__ void gemm_phase(LAS unsigned char* lds, const int tid_in, const int lda, const int ldb, const Sched& S, const Epi& E) {
;     ...
;         for (int t = 0; t < nt; t += 2) {
;             const bool last = (t == nt - 2);
;             const char* a1 = cA + (size_t)(t + 1) * kstep;
;             const char* a2 = last ? nA : cA + (size_t)(t + 2) * kstep; const char* b2 = last ? nB : cB + (size_t)(t + 2) * kstep;
;             const char* a3 = a2 + kstep; const char* b3 = b2 + kstep;
;             PG8_LDB(B0, 0, 0); PG8_LDB(B1, 0, 1); PG8_SCHED; PG8_LDA(At, 0, 0); PG8_STAGE(PG8_SA(1, 1), a1 + hstepA, voffA);
;             PG8_WAIT_V(8); PG8_WAIT_L(0); PG8_BAR; PG8_MMA(0, 0, At, B0); PG8_MMA(0, 1, At, B1); PG8_BAR; PG8_SCHED;
;             PG8_LDA(At, 0, 1); PG8_STAGE(PG8_SB(0, 0), b2, voffB); PG8_STAGE(PG8_SB(0, 1), b2 + hstepB, voffB); PG8_STAGE(PG8_SA(0, 0), a2, voffA);
.LBB0_1026:
	s_waitcnt lgkmcnt(0)
	ds_read_b128 v[128:131], v214
	ds_read_b128 v[132:135], v214 offset:1024
	ds_read_b128 v[136:139], v214 offset:2048
	ds_read_b128 v[140:143], v214 offset:3072
	ds_read_b128 v[144:147], v215
	ds_read_b128 v[148:151], v215 offset:1024
	ds_read_b128 v[152:155], v215 offset:2048
	ds_read_b128 v[156:159], v215 offset:3072
	s_add_i32 s80, s62, 2
	s_add_u32 s63, s60, 0xfff80080
	s_addc_u32 s64, s61, -1
	s_cmp_eq_u32 s86, s62
	s_cselect_b32 s62, s85, s88
	s_cselect_b32 s65, s16, s64
	s_cselect_b32 s64, s59, s63
	s_cselect_b32 s63, s79, s89
	v_lshl_add_u64 v[204:205], s[60:61], 0, v[188:189]
	s_add_i32 m0, s44, 0xc000
	ds_read_b128 v[160:163], v216
	ds_read_b128 v[164:167], v216 offset:1024
	ds_read_b128 v[168:171], v216 offset:2048
	ds_read_b128 v[172:175], v216 offset:3072
	ds_read_b128 v[192:195], v216 offset:4096
	ds_read_b128 v[196:199], v216 offset:5120
	ds_read_b128 v[200:203], v216 offset:6144
	ds_read_b128 v[218:221], v216 offset:7168
	global_load_lds_dwordx4 v[204:205], off
	v_lshl_add_u64 v[204:205], s[60:61], 0, v[190:191]
	s_add_i32 m0, s44, 0xe000
	s_nop 0
	global_load_lds_dwordx4 v[204:205], off
	s_nop 0
	s_waitcnt vmcnt(8)
	s_waitcnt lgkmcnt(0)
	s_barrier
	s_setprio 1
	s_waitcnt lgkmcnt(0)
	v_mfma_f32_16x16x32_bf16 v[124:127], v[128:131], v[160:163], v[124:127]
	v_mfma_f32_16x16x32_bf16 v[120:123], v[136:139], v[160:163], v[120:123]
	v_mfma_f32_16x16x32_bf16 v[104:107], v[136:139], v[168:171], v[104:107]
	v_mfma_f32_16x16x32_bf16 v[108:111], v[128:131], v[168:171], v[108:111]
	v_mfma_f32_16x16x32_bf16 v[92:95], v[128:131], v[192:195], v[92:95]
	v_mfma_f32_16x16x32_bf16 v[88:91], v[136:139], v[192:195], v[88:91]
	v_mfma_f32_16x16x32_bf16 v[72:75], v[136:139], v[200:203], v[72:75]
	v_mfma_f32_16x16x32_bf16 v[76:79], v[128:131], v[200:203], v[76:79]
	v_mfma_f32_16x16x32_bf16 v[124:127], v[132:135], v[164:167], v[124:127]
	v_mfma_f32_16x16x32_bf16 v[120:123], v[140:143], v[164:167], v[120:123]
	v_mfma_f32_16x16x32_bf16 v[104:107], v[140:143], v[172:175], v[104:107]
	v_mfma_f32_16x16x32_bf16 v[108:111], v[132:135], v[172:175], v[108:111]
	v_mfma_f32_16x16x32_bf16 v[92:95], v[132:135], v[196:199], v[92:95]
	v_mfma_f32_16x16x32_bf16 v[88:91], v[140:143], v[196:199], v[88:91]
	v_mfma_f32_16x16x32_bf16 v[72:75], v[140:143], v[218:221], v[72:75]
	v_mfma_f32_16x16x32_bf16 v[76:79], v[132:135], v[218:221], v[76:79]
	s_setprio 0
	s_setprio 1
	v_mfma_f32_16x16x32_bf16 v[116:119], v[144:147], v[160:163], v[116:119]
	v_mfma_f32_16x16x32_bf16 v[112:115], v[152:155], v[160:163], v[112:115]
	v_mfma_f32_16x16x32_bf16 v[96:99], v[152:155], v[168:171], v[96:99]
	v_mfma_f32_16x16x32_bf16 v[100:103], v[144:147], v[168:171], v[100:103]
	v_mfma_f32_16x16x32_bf16 v[84:87], v[144:147], v[192:195], v[84:87]
	v_mfma_f32_16x16x32_bf16 v[80:83], v[152:155], v[192:195], v[80:83]
	v_mfma_f32_16x16x32_bf16 v[64:67], v[152:155], v[200:203], v[64:67]
	v_mfma_f32_16x16x32_bf16 v[68:71], v[144:147], v[200:203], v[68:71]
	v_mfma_f32_16x16x32_bf16 v[116:119], v[148:151], v[164:167], v[116:119]
	v_mfma_f32_16x16x32_bf16 v[112:115], v[156:159], v[164:167], v[112:115]
	v_mfma_f32_16x16x32_bf16 v[96:99], v[156:159], v[172:175], v[96:99]
	v_mfma_f32_16x16x32_bf16 v[100:103], v[148:151], v[172:175], v[100:103]
	v_mfma_f32_16x16x32_bf16 v[84:87], v[148:151], v[196:199], v[84:87]
	v_mfma_f32_16x16x32_bf16 v[80:83], v[156:159], v[196:199], v[80:83]
	v_mfma_f32_16x16x32_bf16 v[64:67], v[156:159], v[218:221], v[64:67]
	v_mfma_f32_16x16x32_bf16 v[68:71], v[148:151], v[218:221], v[68:71]
	s_setprio 0
	s_barrier
	s_add_i32 s90, s72, s35
	v_lshl_add_u64 v[204:205], s[62:63], 0, v[178:179]
	s_mov_b32 m0, s90
	ds_read_b128 v[160:163], v216 offset:16384
	ds_read_b128 v[164:167], v216 offset:17408
	ds_read_b128 v[168:171], v216 offset:18432
	ds_read_b128 v[172:175], v216 offset:19456
	ds_read_b128 v[192:195], v216 offset:20480
	ds_read_b128 v[196:199], v216 offset:21504
	ds_read_b128 v[200:203], v216 offset:22528
	ds_read_b128 v[218:221], v216 offset:23552
	global_load_lds_dwordx4 v[204:205], off
	s_add_i32 m0, s90, 0x2000
	s_add_u32 s90, s62, 0x80000
	v_lshl_add_u64 v[222:223], s[62:63], 0, v[182:183]
	s_addc_u32 s91, s63, 0
	s_add_i32 s92, s73, s35
	global_load_lds_dwordx4 v[222:223], off
	v_lshl_add_u64 v[226:227], s[90:91], 0, v[178:179]
	s_mov_b32 m0, s92
	v_lshl_add_u64 v[228:229], s[64:65], 0, v[180:181]
	global_load_lds_dwordx4 v[226:227], off
	v_lshl_add_u64 v[226:227], s[90:91], 0, v[182:183]
	s_add_i32 m0, s92, 0x2000
	s_nop 0
	global_load_lds_dwordx4 v[226:227], off
	v_lshl_add_u64 v[226:227], s[64:65], 0, v[176:177]
	s_mov_b32 m0, s44
	s_nop 0
	global_load_lds_dwordx4 v[226:227], off
	s_mov_b32 m0, s45
	s_nop 0
	global_load_lds_dwordx4 v[228:229], off
	s_nop 0
	s_waitcnt vmcnt(8)
	s_waitcnt lgkmcnt(0)
	s_barrier
; #define PG8_STAGE(bufoff, gbase, voff) do { _Pragma("unroll") for (int _i = 0; _i < 2; ++_i) \
;         __builtin_amdgcn_global_load_lds((const unsigned*)((const char*)(gbase) + (voff)[_i]), (LAS unsigned*)(lds + (bufoff) + ldsw + _i * 8192), 16, 0, 0); } while (0)
; #define PG8_LDA(dst, b, h) do { _Pragma("unroll") for (int m = 0; m < 4; ++m) _Pragma("unroll") for (int k = 0; k < 2; ++k) dst[m][k] = *(const LAS bf16x8*)(lds + PG8_SA(b, h) + aoff + m * 2048 + k * 1024); } while (0)
; #define PG8_LDB(dst, b, h) do { _Pragma("unroll") for (int n = 0; n < 2; ++n) _Pragma("unroll") for (int k = 0; k < 2; ++k) dst[n][k] = *(const LAS bf16x8*)(lds + PG8_SB(b, h) + boff + n * 2048 + k * 1024); } while (0)
; #define PG8_MMA(ai, bj, At, Bt) do { __builtin_amdgcn_s_setprio(1); _Pragma("unroll") for (int m = 0; m < 4; ++m) _Pragma("unroll") for (int n = 0; n < 2; ++n) _Pragma("unroll") for (int k = 0; k < 2; ++k) \
;         acc[ai][bj][m][n] = __builtin_amdgcn_mfma_f32_16x16x32_bf16(Bt[n][k], At[m][k], acc[ai][bj][m][n], 0, 0, 0); __builtin_amdgcn_s_setprio(0); } while (0)
; #define PG8_WAIT_V(n) asm volatile("s_waitcnt vmcnt(" #n ")" ::: "memory")
; #define PG8_WAIT_L(n) asm volatile("s_waitcnt lgkmcnt(" #n ")" ::: "memory")
; #define PG8_BAR __builtin_amdgcn_s_barrier()
; #define PG8_SCHED __builtin_amdgcn_sched_barrier(0)
; template <int FIXED_NT  , class Epi, class Sched>
; __device__ __forceinline__ void gemm_phase(LAS unsigned char* lds, const int tid_in, const int lda, const int ldb, const Sched& S, const Epi& E) {
;     ...
;             PG8_WAIT_V(8); PG8_WAIT_L(0); PG8_BAR; PG8_MMA(1, 0, At, B0); PG8_MMA(1, 1, At, B1); PG8_BAR; PG8_SCHED;
;             PG8_LDB(B0, 1, 0); PG8_LDB(B1, 1, 1); PG8_SCHED; PG8_LDA(At, 1, 0); PG8_STAGE(PG8_SA(0, 1), a2 + hstepA, voffA);
;             PG8_WAIT_V(8); PG8_WAIT_L(0); PG8_BAR; PG8_MMA(0, 0, At, B0); PG8_MMA(0, 1, At, B1); PG8_BAR; PG8_SCHED;
	s_setprio 1
	s_waitcnt lgkmcnt(0)
	v_mfma_f32_16x16x32_bf16 v[60:63], v[128:131], v[160:163], v[60:63]
	v_mfma_f32_16x16x32_bf16 v[56:59], v[136:139], v[160:163], v[56:59]
	v_mfma_f32_16x16x32_bf16 v[40:43], v[136:139], v[168:171], v[40:43]
	v_mfma_f32_16x16x32_bf16 v[44:47], v[128:131], v[168:171], v[44:47]
	v_mfma_f32_16x16x32_bf16 v[28:31], v[128:131], v[192:195], v[28:31]
	v_mfma_f32_16x16x32_bf16 v[24:27], v[136:139], v[192:195], v[24:27]
	v_mfma_f32_16x16x32_bf16 v[8:11], v[136:139], v[200:203], v[8:11]
	v_mfma_f32_16x16x32_bf16 v[12:15], v[128:131], v[200:203], v[12:15]
	v_mfma_f32_16x16x32_bf16 v[60:63], v[132:135], v[164:167], v[60:63]
	v_mfma_f32_16x16x32_bf16 v[56:59], v[140:143], v[164:167], v[56:59]
	v_mfma_f32_16x16x32_bf16 v[40:43], v[140:143], v[172:175], v[40:43]
	v_mfma_f32_16x16x32_bf16 v[44:47], v[132:135], v[172:175], v[44:47]
	v_mfma_f32_16x16x32_bf16 v[28:31], v[132:135], v[196:199], v[28:31]
	v_mfma_f32_16x16x32_bf16 v[24:27], v[140:143], v[196:199], v[24:27]
	v_mfma_f32_16x16x32_bf16 v[8:11], v[140:143], v[218:221], v[8:11]
	v_mfma_f32_16x16x32_bf16 v[12:15], v[132:135], v[218:221], v[12:15]
	s_setprio 0
	s_setprio 1
	v_mfma_f32_16x16x32_bf16 v[52:55], v[144:147], v[160:163], v[52:55]
	v_mfma_f32_16x16x32_bf16 v[48:51], v[152:155], v[160:163], v[48:51]
	v_mfma_f32_16x16x32_bf16 v[32:35], v[152:155], v[168:171], v[32:35]
	v_mfma_f32_16x16x32_bf16 v[36:39], v[144:147], v[168:171], v[36:39]
	v_mfma_f32_16x16x32_bf16 v[20:23], v[144:147], v[192:195], v[20:23]
	v_mfma_f32_16x16x32_bf16 v[16:19], v[152:155], v[192:195], v[16:19]
	v_mfma_f32_16x16x32_bf16 v[0:3], v[152:155], v[200:203], v[0:3]
	v_mfma_f32_16x16x32_bf16 v[4:7], v[144:147], v[200:203], v[4:7]
	v_mfma_f32_16x16x32_bf16 v[52:55], v[148:151], v[164:167], v[52:55]
	v_mfma_f32_16x16x32_bf16 v[48:51], v[156:159], v[164:167], v[48:51]
	v_mfma_f32_16x16x32_bf16 v[32:35], v[156:159], v[172:175], v[32:35]
	v_mfma_f32_16x16x32_bf16 v[36:39], v[148:151], v[172:175], v[36:39]
	v_mfma_f32_16x16x32_bf16 v[20:23], v[148:151], v[196:199], v[20:23]
	v_mfma_f32_16x16x32_bf16 v[16:19], v[156:159], v[196:199], v[16:19]
	v_mfma_f32_16x16x32_bf16 v[0:3], v[156:159], v[218:221], v[0:3]
	v_mfma_f32_16x16x32_bf16 v[4:7], v[148:151], v[218:221], v[4:7]
	s_setprio 0
	s_barrier
	s_add_i32 s90, 0, 0x18000
	s_add_i32 s91, 0, 0x1c000
	v_add_u32_e32 v140, s90, v206
	v_add_u32_e32 v156, s91, v206
	ds_read_b128 v[128:131], v140
	ds_read_b128 v[132:135], v140 offset:1024
	ds_read_b128 v[136:139], v140 offset:2048
	ds_read_b128 v[140:143], v140 offset:3072
	ds_read_b128 v[144:147], v156
	ds_read_b128 v[148:151], v156 offset:1024
	ds_read_b128 v[152:155], v156 offset:2048
	ds_read_b128 v[156:159], v156 offset:3072
	s_add_u32 s64, s64, 0x80000
	s_addc_u32 s65, s65, 0
	s_mov_b32 m0, s66
	v_lshl_add_u64 v[230:231], s[64:65], 0, v[176:177]
	ds_read_b128 v[160:163], v216 offset:32768
	ds_read_b128 v[164:167], v216 offset:33792
	ds_read_b128 v[168:171], v216 offset:34816
	ds_read_b128 v[172:175], v216 offset:35840
	ds_read_b128 v[192:195], v216 offset:36864
	ds_read_b128 v[196:199], v216 offset:37888
	ds_read_b128 v[200:203], v216 offset:38912
	ds_read_b128 v[218:221], v216 offset:39936
	global_load_lds_dwordx4 v[230:231], off
	v_lshl_add_u64 v[230:231], s[64:65], 0, v[180:181]
	s_mov_b32 m0, s67
	s_nop 0
	global_load_lds_dwordx4 v[230:231], off
	s_nop 0
	s_waitcnt vmcnt(8)
	s_waitcnt lgkmcnt(0)
	s_barrier
	s_setprio 1
	s_waitcnt lgkmcnt(0)
	v_mfma_f32_16x16x32_bf16 v[124:127], v[128:131], v[160:163], v[124:127]
	v_mfma_f32_16x16x32_bf16 v[120:123], v[136:139], v[160:163], v[120:123]
	v_mfma_f32_16x16x32_bf16 v[104:107], v[136:139], v[168:171], v[104:107]
	v_mfma_f32_16x16x32_bf16 v[108:111], v[128:131], v[168:171], v[108:111]
	v_mfma_f32_16x16x32_bf16 v[92:95], v[128:131], v[192:195], v[92:95]
	v_mfma_f32_16x16x32_bf16 v[88:91], v[136:139], v[192:195], v[88:91]
	v_mfma_f32_16x16x32_bf16 v[72:75], v[136:139], v[200:203], v[72:75]
	v_mfma_f32_16x16x32_bf16 v[76:79], v[128:131], v[200:203], v[76:79]
	v_mfma_f32_16x16x32_bf16 v[124:127], v[132:135], v[164:167], v[124:127]
	v_mfma_f32_16x16x32_bf16 v[120:123], v[140:143], v[164:167], v[120:123]
	v_mfma_f32_16x16x32_bf16 v[104:107], v[140:143], v[172:175], v[104:107]
	v_mfma_f32_16x16x32_bf16 v[108:111], v[132:135], v[172:175], v[108:111]
	v_mfma_f32_16x16x32_bf16 v[92:95], v[132:135], v[196:199], v[92:95]
	v_mfma_f32_16x16x32_bf16 v[88:91], v[140:143], v[196:199], v[88:91]
	v_mfma_f32_16x16x32_bf16 v[72:75], v[140:143], v[218:221], v[72:75]
	v_mfma_f32_16x16x32_bf16 v[76:79], v[132:135], v[218:221], v[76:79]
	s_setprio 0
	s_setprio 1
	v_mfma_f32_16x16x32_bf16 v[116:119], v[144:147], v[160:163], v[116:119]
	v_mfma_f32_16x16x32_bf16 v[112:115], v[152:155], v[160:163], v[112:115]
	v_mfma_f32_16x16x32_bf16 v[96:99], v[152:155], v[168:171], v[96:99]
	v_mfma_f32_16x16x32_bf16 v[100:103], v[144:147], v[168:171], v[100:103]
	v_mfma_f32_16x16x32_bf16 v[84:87], v[144:147], v[192:195], v[84:87]
	v_mfma_f32_16x16x32_bf16 v[80:83], v[152:155], v[192:195], v[80:83]
	v_mfma_f32_16x16x32_bf16 v[64:67], v[152:155], v[200:203], v[64:67]
	v_mfma_f32_16x16x32_bf16 v[68:71], v[144:147], v[200:203], v[68:71]
	v_mfma_f32_16x16x32_bf16 v[116:119], v[148:151], v[164:167], v[116:119]
	v_mfma_f32_16x16x32_bf16 v[112:115], v[156:159], v[164:167], v[112:115]
	v_mfma_f32_16x16x32_bf16 v[96:99], v[156:159], v[172:175], v[96:99]
	v_mfma_f32_16x16x32_bf16 v[100:103], v[148:151], v[172:175], v[100:103]
	v_mfma_f32_16x16x32_bf16 v[84:87], v[148:151], v[196:199], v[84:87]
	v_mfma_f32_16x16x32_bf16 v[80:83], v[156:159], v[196:199], v[80:83]
	v_mfma_f32_16x16x32_bf16 v[64:67], v[156:159], v[218:221], v[64:67]
	v_mfma_f32_16x16x32_bf16 v[68:71], v[148:151], v[218:221], v[68:71]
	s_setprio 0
	s_barrier
; #define PG8_STAGE(bufoff, gbase, voff) do { _Pragma("unroll") for (int _i = 0; _i < 2; ++_i) \
;         __builtin_amdgcn_global_load_lds((const unsigned*)((const char*)(gbase) + (voff)[_i]), (LAS unsigned*)(lds + (bufoff) + ldsw + _i * 8192), 16, 0, 0); } while (0)
; #define PG8_LDA(dst, b, h) do { _Pragma("unroll") for (int m = 0; m < 4; ++m) _Pragma("unroll") for (int k = 0; k < 2; ++k) dst[m][k] = *(const LAS bf16x8*)(lds + PG8_SA(b, h) + aoff + m * 2048 + k * 1024); } while (0)
; #define PG8_MMA(ai, bj, At, Bt) do { __builtin_amdgcn_s_setprio(1); _Pragma("unroll") for (int m = 0; m < 4; ++m) _Pragma("unroll") for (int n = 0; n < 2; ++n) _Pragma("unroll") for (int k = 0; k < 2; ++k) \
;         acc[ai][bj][m][n] = __builtin_amdgcn_mfma_f32_16x16x32_bf16(Bt[n][k], At[m][k], acc[ai][bj][m][n], 0, 0, 0); __builtin_amdgcn_s_setprio(0); } while (0)
; #define PG8_WAIT_V(n) asm volatile("s_waitcnt vmcnt(" #n ")" ::: "memory")
; #define PG8_WAIT_L(n) asm volatile("s_waitcnt lgkmcnt(" #n ")" ::: "memory")
; #define PG8_BAR __builtin_amdgcn_s_barrier()
; #define PG8_SCHED __builtin_amdgcn_sched_barrier(0)
; template <int FIXED_NT  , class Epi, class Sched>
; __device__ __forceinline__ void gemm_phase(LAS unsigned char* lds, const int tid_in, const int lda, const int ldb, const Sched& S, const Epi& E) {
;     ...
;             PG8_LDA(At, 1, 1); PG8_STAGE(PG8_SB(1, 0), b3, voffB); PG8_STAGE(PG8_SB(1, 1), b3 + hstepB, voffB); PG8_STAGE(PG8_SA(1, 0), a3, voffA);
;             PG8_WAIT_V(8); PG8_WAIT_L(0); PG8_BAR; PG8_MMA(1, 0, At, B0); PG8_MMA(1, 1, At, B1); PG8_BAR; PG8_SCHED;
;         }
	s_add_i32 s64, s90, s35
	v_lshl_add_u64 v[204:205], v[204:205], 0, s[22:23]
	s_mov_b32 m0, s64
	ds_read_b128 v[160:163], v216 offset:49152
	ds_read_b128 v[164:167], v216 offset:50176
	ds_read_b128 v[168:171], v216 offset:51200
	ds_read_b128 v[172:175], v216 offset:52224
	ds_read_b128 v[192:195], v216 offset:53248
	ds_read_b128 v[196:199], v216 offset:54272
	ds_read_b128 v[200:203], v216 offset:55296
	ds_read_b128 v[218:221], v216 offset:56320
	global_load_lds_dwordx4 v[204:205], off
	s_add_i32 m0, s64, 0x2000
	s_add_u32 s62, s62, 0x80080
	v_lshl_add_u64 v[204:205], v[222:223], 0, s[22:23]
	s_addc_u32 s63, s63, 0
	s_add_i32 s64, s91, s35
	global_load_lds_dwordx4 v[204:205], off
	v_lshl_add_u64 v[204:205], s[62:63], 0, v[178:179]
	s_mov_b32 m0, s64
	s_nop 0
	global_load_lds_dwordx4 v[204:205], off
	v_lshl_add_u64 v[204:205], s[62:63], 0, v[182:183]
	s_add_i32 m0, s64, 0x2000
	s_nop 0
	global_load_lds_dwordx4 v[204:205], off
	v_lshl_add_u64 v[204:205], v[226:227], 0, s[22:23]
	s_mov_b32 m0, s69
	s_nop 0
	global_load_lds_dwordx4 v[204:205], off
	v_lshl_add_u64 v[204:205], v[228:229], 0, s[22:23]
	s_mov_b32 m0, s70
	s_nop 0
	global_load_lds_dwordx4 v[204:205], off
	s_waitcnt vmcnt(8)
	s_waitcnt lgkmcnt(0)
	s_barrier
	s_setprio 1
	s_waitcnt lgkmcnt(0)
	v_mfma_f32_16x16x32_bf16 v[60:63], v[128:131], v[160:163], v[60:63]
	v_mfma_f32_16x16x32_bf16 v[56:59], v[136:139], v[160:163], v[56:59]
	v_mfma_f32_16x16x32_bf16 v[40:43], v[136:139], v[168:171], v[40:43]
	v_mfma_f32_16x16x32_bf16 v[44:47], v[128:131], v[168:171], v[44:47]
	v_mfma_f32_16x16x32_bf16 v[28:31], v[128:131], v[192:195], v[28:31]
	v_mfma_f32_16x16x32_bf16 v[24:27], v[136:139], v[192:195], v[24:27]
	v_mfma_f32_16x16x32_bf16 v[8:11], v[136:139], v[200:203], v[8:11]
	v_mfma_f32_16x16x32_bf16 v[12:15], v[128:131], v[200:203], v[12:15]
	v_mfma_f32_16x16x32_bf16 v[60:63], v[132:135], v[164:167], v[60:63]
	v_mfma_f32_16x16x32_bf16 v[56:59], v[140:143], v[164:167], v[56:59]
	v_mfma_f32_16x16x32_bf16 v[40:43], v[140:143], v[172:175], v[40:43]
	v_mfma_f32_16x16x32_bf16 v[44:47], v[132:135], v[172:175], v[44:47]
	v_mfma_f32_16x16x32_bf16 v[28:31], v[132:135], v[196:199], v[28:31]
	v_mfma_f32_16x16x32_bf16 v[24:27], v[140:143], v[196:199], v[24:27]
	v_mfma_f32_16x16x32_bf16 v[8:11], v[140:143], v[218:221], v[8:11]
	v_mfma_f32_16x16x32_bf16 v[12:15], v[132:135], v[218:221], v[12:15]
	s_setprio 0
	s_setprio 1
	v_mfma_f32_16x16x32_bf16 v[52:55], v[144:147], v[160:163], v[52:55]
	v_mfma_f32_16x16x32_bf16 v[48:51], v[152:155], v[160:163], v[48:51]
	v_mfma_f32_16x16x32_bf16 v[32:35], v[152:155], v[168:171], v[32:35]
	v_mfma_f32_16x16x32_bf16 v[36:39], v[144:147], v[168:171], v[36:39]
	v_mfma_f32_16x16x32_bf16 v[20:23], v[144:147], v[192:195], v[20:23]
	v_mfma_f32_16x16x32_bf16 v[16:19], v[152:155], v[192:195], v[16:19]
	v_mfma_f32_16x16x32_bf16 v[0:3], v[152:155], v[200:203], v[0:3]
	v_mfma_f32_16x16x32_bf16 v[4:7], v[144:147], v[200:203], v[4:7]
	v_mfma_f32_16x16x32_bf16 v[52:55], v[148:151], v[164:167], v[52:55]
	v_mfma_f32_16x16x32_bf16 v[48:51], v[156:159], v[164:167], v[48:51]
	v_mfma_f32_16x16x32_bf16 v[32:35], v[156:159], v[172:175], v[32:35]
	v_mfma_f32_16x16x32_bf16 v[36:39], v[148:151], v[172:175], v[36:39]
	v_mfma_f32_16x16x32_bf16 v[20:23], v[148:151], v[196:199], v[20:23]
	v_mfma_f32_16x16x32_bf16 v[16:19], v[156:159], v[196:199], v[16:19]
	v_mfma_f32_16x16x32_bf16 v[0:3], v[156:159], v[218:221], v[0:3]
	v_mfma_f32_16x16x32_bf16 v[4:7], v[148:151], v[218:221], v[4:7]
	s_setprio 0
	s_barrier
	s_add_u32 s60, s60, 0x100
	s_addc_u32 s61, s61, 0
	s_add_u32 s88, s88, 0x100
	s_addc_u32 s89, s89, 0
	s_cmp_ge_i32 s80, s33
	s_mov_b32 s62, s80
	s_cbranch_scc0 .LBB0_1026
	s_and_b64 vcc, exec, s[24:25]
	s_cbranch_vccz .LBB0_1032

; #define PG8_STAGE(bufoff, gbase, voff) do { _Pragma("unroll") for (int _i = 0; _i < 2; ++_i) \
;         __builtin_amdgcn_global_load_lds((const unsigned*)((const char*)(gbase) + (voff)[_i]), (LAS unsigned*)(lds + (bufoff) + ldsw + _i * 8192), 16, 0, 0); } while (0)
; #define PG8_LDA(dst, b, h) do { _Pragma("unroll") for (int m = 0; m < 4; ++m) _Pragma("unroll") for (int k = 0; k < 2; ++k) dst[m][k] = *(const LAS bf16x8*)(lds + PG8_SA(b, h) + aoff + m * 2048 + k * 1024); } while (0)
; #define PG8_LDB(dst, b, h) do { _Pragma("unroll") for (int n = 0; n < 2; ++n) _Pragma("unroll") for (int k = 0; k < 2; ++k) dst[n][k] = *(const LAS bf16x8*)(lds + PG8_SB(b, h) + boff + n * 2048 + k * 1024); } while (0)
; #define PG8_MMA(ai, bj, At, Bt) do { __builtin_amdgcn_s_setprio(1); _Pragma("unroll") for (int m = 0; m < 4; ++m) _Pragma("unroll") for (int n = 0; n < 2; ++n) _Pragma("unroll") for (int k = 0; k < 2; ++k) \
;         acc[ai][bj][m][n] = __builtin_amdgcn_mfma_f32_16x16x32_bf16(Bt[n][k], At[m][k], acc[ai][bj][m][n], 0, 0, 0); __builtin_amdgcn_s_setprio(0); } while (0)
; #define PG8_WAIT_V(n) asm volatile("s_waitcnt vmcnt(" #n ")" ::: "memory")
; #define PG8_WAIT_L(n) asm volatile("s_waitcnt lgkmcnt(" #n ")" ::: "memory")
; #define PG8_BAR __builtin_amdgcn_s_barrier()
; #define PG8_SCHED __builtin_amdgcn_sched_barrier(0)
; template <int FIXED_NT  , class Epi, class Sched>
; __device__ __forceinline__ void gemm_phase(LAS unsigned char* lds, const int tid_in, const int lda, const int ldb, const Sched& S, const Epi& E) {
;     ...
;         for (int t = 0; t < nt; t += 2) {
;             const bool last = (t == nt - 2);
;             const char* a1 = cA + (size_t)(t + 1) * kstep;
;             const char* a2 = last ? nA : cA + (size_t)(t + 2) * kstep; const char* b2 = last ? nB : cB + (size_t)(t + 2) * kstep;
;             const char* a3 = a2 + kstep; const char* b3 = b2 + kstep;
;             PG8_LDB(B0, 0, 0); PG8_LDB(B1, 0, 1); PG8_SCHED; PG8_LDA(At, 0, 0); PG8_STAGE(PG8_SA(1, 1), a1 + hstepA, voffA);
;             PG8_WAIT_V(8); PG8_WAIT_L(0); PG8_BAR; PG8_MMA(0, 0, At, B0); PG8_MMA(0, 1, At, B1); PG8_BAR; PG8_SCHED;
;             PG8_LDA(At, 0, 1); PG8_STAGE(PG8_SB(0, 0), b2, voffB); PG8_STAGE(PG8_SB(0, 1), b2 + hstepB, voffB); PG8_STAGE(PG8_SA(0, 0), a2, voffA);
.LBB0_1178:
	ds_read_b128 v[154:157], v147
	ds_read_b128 v[158:161], v147 offset:1024
	ds_read_b128 v[162:165], v147 offset:2048
	ds_read_b128 v[166:169], v147 offset:3072
	ds_read_b128 v[170:173], v149
	ds_read_b128 v[174:177], v149 offset:1024
	ds_read_b128 v[178:181], v149 offset:2048
	ds_read_b128 v[182:185], v149 offset:3072
	s_add_i32 s64, s28, 2
	s_add_u32 s29, s24, 0xfff80080
	s_addc_u32 s30, s25, -1
	s_cmp_eq_u32 s59, s28
	s_cselect_b32 s28, s20, s15
	s_cselect_b32 s31, s17, s30
	s_cselect_b32 s30, s16, s29
	s_cselect_b32 s29, s21, s63
	v_lshl_add_u64 v[218:219], s[24:25], 0, v[138:139]
	s_add_i32 m0, s45, 0xc000
	ds_read_b128 v[186:189], v151
	ds_read_b128 v[190:193], v151 offset:1024
	ds_read_b128 v[194:197], v151 offset:2048
	ds_read_b128 v[198:201], v151 offset:3072
	ds_read_b128 v[202:205], v151 offset:4096
	ds_read_b128 v[206:209], v151 offset:5120
	ds_read_b128 v[210:213], v151 offset:6144
	ds_read_b128 v[214:217], v151 offset:7168
	global_load_lds_dwordx4 v[218:219], off
	v_lshl_add_u64 v[218:219], s[24:25], 0, v[140:141]
	s_add_i32 m0, s45, 0xe000
	s_nop 0
	global_load_lds_dwordx4 v[218:219], off
	s_nop 0
	s_waitcnt vmcnt(8)
	s_waitcnt lgkmcnt(0)
	s_barrier
	s_setprio 1
	s_waitcnt lgkmcnt(0)
	v_mfma_f32_16x16x32_bf16 v[124:127], v[154:157], v[186:189], v[124:127]
	v_mfma_f32_16x16x32_bf16 v[120:123], v[162:165], v[186:189], v[120:123]
	v_mfma_f32_16x16x32_bf16 v[104:107], v[162:165], v[194:197], v[104:107]
	v_mfma_f32_16x16x32_bf16 v[108:111], v[154:157], v[194:197], v[108:111]
	v_mfma_f32_16x16x32_bf16 v[92:95], v[154:157], v[202:205], v[92:95]
	v_mfma_f32_16x16x32_bf16 v[88:91], v[162:165], v[202:205], v[88:91]
	v_mfma_f32_16x16x32_bf16 v[72:75], v[162:165], v[210:213], v[72:75]
	v_mfma_f32_16x16x32_bf16 v[76:79], v[154:157], v[210:213], v[76:79]
	v_mfma_f32_16x16x32_bf16 v[124:127], v[158:161], v[190:193], v[124:127]
	v_mfma_f32_16x16x32_bf16 v[120:123], v[166:169], v[190:193], v[120:123]
	v_mfma_f32_16x16x32_bf16 v[104:107], v[166:169], v[198:201], v[104:107]
	v_mfma_f32_16x16x32_bf16 v[108:111], v[158:161], v[198:201], v[108:111]
	v_mfma_f32_16x16x32_bf16 v[92:95], v[158:161], v[206:209], v[92:95]
	v_mfma_f32_16x16x32_bf16 v[88:91], v[166:169], v[206:209], v[88:91]
	v_mfma_f32_16x16x32_bf16 v[72:75], v[166:169], v[214:217], v[72:75]
	v_mfma_f32_16x16x32_bf16 v[76:79], v[158:161], v[214:217], v[76:79]
	s_setprio 0
	s_setprio 1
	v_mfma_f32_16x16x32_bf16 v[116:119], v[170:173], v[186:189], v[116:119]
	v_mfma_f32_16x16x32_bf16 v[112:115], v[178:181], v[186:189], v[112:115]
	v_mfma_f32_16x16x32_bf16 v[96:99], v[178:181], v[194:197], v[96:99]
	v_mfma_f32_16x16x32_bf16 v[100:103], v[170:173], v[194:197], v[100:103]
	v_mfma_f32_16x16x32_bf16 v[84:87], v[170:173], v[202:205], v[84:87]
	v_mfma_f32_16x16x32_bf16 v[80:83], v[178:181], v[202:205], v[80:83]
	v_mfma_f32_16x16x32_bf16 v[64:67], v[178:181], v[210:213], v[64:67]
	v_mfma_f32_16x16x32_bf16 v[68:71], v[170:173], v[210:213], v[68:71]
	v_mfma_f32_16x16x32_bf16 v[116:119], v[174:177], v[190:193], v[116:119]
	v_mfma_f32_16x16x32_bf16 v[112:115], v[182:185], v[190:193], v[112:115]
	v_mfma_f32_16x16x32_bf16 v[96:99], v[182:185], v[198:201], v[96:99]
	v_mfma_f32_16x16x32_bf16 v[100:103], v[174:177], v[198:201], v[100:103]
	v_mfma_f32_16x16x32_bf16 v[84:87], v[174:177], v[206:209], v[84:87]
	v_mfma_f32_16x16x32_bf16 v[80:83], v[182:185], v[206:209], v[80:83]
	v_mfma_f32_16x16x32_bf16 v[64:67], v[182:185], v[214:217], v[64:67]
	v_mfma_f32_16x16x32_bf16 v[68:71], v[174:177], v[214:217], v[68:71]
	s_setprio 0
	s_barrier
	s_add_i32 s65, s60, s35
	v_lshl_add_u64 v[218:219], s[28:29], 0, v[132:133]
	s_mov_b32 m0, s65
	ds_read_b128 v[186:189], v151 offset:16384
	ds_read_b128 v[190:193], v151 offset:17408
	ds_read_b128 v[194:197], v151 offset:18432
	ds_read_b128 v[198:201], v151 offset:19456
	ds_read_b128 v[202:205], v151 offset:20480
	ds_read_b128 v[206:209], v151 offset:21504
	ds_read_b128 v[210:213], v151 offset:22528
	ds_read_b128 v[214:217], v151 offset:23552
	global_load_lds_dwordx4 v[218:219], off
	s_add_i32 m0, s65, 0x2000
	s_add_u32 s66, s28, 0x80000
	v_lshl_add_u64 v[220:221], s[28:29], 0, v[128:129]
	s_addc_u32 s67, s29, 0
	s_add_i32 s65, s61, s35
	global_load_lds_dwordx4 v[220:221], off
	v_lshl_add_u64 v[222:223], s[66:67], 0, v[132:133]
	s_mov_b32 m0, s65
	v_lshl_add_u64 v[226:227], s[30:31], 0, v[130:131]
	global_load_lds_dwordx4 v[222:223], off
	v_lshl_add_u64 v[222:223], s[66:67], 0, v[128:129]
	s_add_i32 m0, s65, 0x2000
	s_nop 0
	global_load_lds_dwordx4 v[222:223], off
	v_lshl_add_u64 v[222:223], s[30:31], 0, v[134:135]
	s_mov_b32 m0, s45
	s_nop 0
	global_load_lds_dwordx4 v[222:223], off
	s_mov_b32 m0, s50
	s_nop 0
	global_load_lds_dwordx4 v[226:227], off
	s_nop 0
	s_waitcnt vmcnt(8)
	s_waitcnt lgkmcnt(0)
	s_barrier
; #define PG8_STAGE(bufoff, gbase, voff) do { _Pragma("unroll") for (int _i = 0; _i < 2; ++_i) \
;         __builtin_amdgcn_global_load_lds((const unsigned*)((const char*)(gbase) + (voff)[_i]), (LAS unsigned*)(lds + (bufoff) + ldsw + _i * 8192), 16, 0, 0); } while (0)
; #define PG8_LDA(dst, b, h) do { _Pragma("unroll") for (int m = 0; m < 4; ++m) _Pragma("unroll") for (int k = 0; k < 2; ++k) dst[m][k] = *(const LAS bf16x8*)(lds + PG8_SA(b, h) + aoff + m * 2048 + k * 1024); } while (0)
; #define PG8_LDB(dst, b, h) do { _Pragma("unroll") for (int n = 0; n < 2; ++n) _Pragma("unroll") for (int k = 0; k < 2; ++k) dst[n][k] = *(const LAS bf16x8*)(lds + PG8_SB(b, h) + boff + n * 2048 + k * 1024); } while (0)
; #define PG8_MMA(ai, bj, At, Bt) do { __builtin_amdgcn_s_setprio(1); _Pragma("unroll") for (int m = 0; m < 4; ++m) _Pragma("unroll") for (int n = 0; n < 2; ++n) _Pragma("unroll") for (int k = 0; k < 2; ++k) \
;         acc[ai][bj][m][n] = __builtin_amdgcn_mfma_f32_16x16x32_bf16(Bt[n][k], At[m][k], acc[ai][bj][m][n], 0, 0, 0); __builtin_amdgcn_s_setprio(0); } while (0)
; #define PG8_WAIT_V(n) asm volatile("s_waitcnt vmcnt(" #n ")" ::: "memory")
; #define PG8_WAIT_L(n) asm volatile("s_waitcnt lgkmcnt(" #n ")" ::: "memory")
; #define PG8_BAR __builtin_amdgcn_s_barrier()
; #define PG8_SCHED __builtin_amdgcn_sched_barrier(0)
; template <int FIXED_NT  , class Epi, class Sched>
; __device__ __forceinline__ void gemm_phase(LAS unsigned char* lds, const int tid_in, const int lda, const int ldb, const Sched& S, const Epi& E) {
;     ...
;             PG8_WAIT_V(8); PG8_WAIT_L(0); PG8_BAR; PG8_MMA(1, 0, At, B0); PG8_MMA(1, 1, At, B1); PG8_BAR; PG8_SCHED;
;             PG8_LDB(B0, 1, 0); PG8_LDB(B1, 1, 1); PG8_SCHED; PG8_LDA(At, 1, 0); PG8_STAGE(PG8_SA(0, 1), a2 + hstepA, voffA);
;             PG8_WAIT_V(8); PG8_WAIT_L(0); PG8_BAR; PG8_MMA(0, 0, At, B0); PG8_MMA(0, 1, At, B1); PG8_BAR; PG8_SCHED;
	s_setprio 1
	s_waitcnt lgkmcnt(0)
	v_mfma_f32_16x16x32_bf16 v[60:63], v[154:157], v[186:189], v[60:63]
	v_mfma_f32_16x16x32_bf16 v[56:59], v[162:165], v[186:189], v[56:59]
	v_mfma_f32_16x16x32_bf16 v[40:43], v[162:165], v[194:197], v[40:43]
	v_mfma_f32_16x16x32_bf16 v[44:47], v[154:157], v[194:197], v[44:47]
	v_mfma_f32_16x16x32_bf16 v[28:31], v[154:157], v[202:205], v[28:31]
	v_mfma_f32_16x16x32_bf16 v[24:27], v[162:165], v[202:205], v[24:27]
	v_mfma_f32_16x16x32_bf16 v[8:11], v[162:165], v[210:213], v[8:11]
	v_mfma_f32_16x16x32_bf16 v[12:15], v[154:157], v[210:213], v[12:15]
	v_mfma_f32_16x16x32_bf16 v[60:63], v[158:161], v[190:193], v[60:63]
	v_mfma_f32_16x16x32_bf16 v[56:59], v[166:169], v[190:193], v[56:59]
	v_mfma_f32_16x16x32_bf16 v[40:43], v[166:169], v[198:201], v[40:43]
	v_mfma_f32_16x16x32_bf16 v[44:47], v[158:161], v[198:201], v[44:47]
	v_mfma_f32_16x16x32_bf16 v[28:31], v[158:161], v[206:209], v[28:31]
	v_mfma_f32_16x16x32_bf16 v[24:27], v[166:169], v[206:209], v[24:27]
	v_mfma_f32_16x16x32_bf16 v[8:11], v[166:169], v[214:217], v[8:11]
	v_mfma_f32_16x16x32_bf16 v[12:15], v[158:161], v[214:217], v[12:15]
	s_setprio 0
	s_setprio 1
	v_mfma_f32_16x16x32_bf16 v[52:55], v[170:173], v[186:189], v[52:55]
	v_mfma_f32_16x16x32_bf16 v[48:51], v[178:181], v[186:189], v[48:51]
	v_mfma_f32_16x16x32_bf16 v[32:35], v[178:181], v[194:197], v[32:35]
	v_mfma_f32_16x16x32_bf16 v[36:39], v[170:173], v[194:197], v[36:39]
	v_mfma_f32_16x16x32_bf16 v[20:23], v[170:173], v[202:205], v[20:23]
	v_mfma_f32_16x16x32_bf16 v[16:19], v[178:181], v[202:205], v[16:19]
	v_mfma_f32_16x16x32_bf16 v[0:3], v[178:181], v[210:213], v[0:3]
	v_mfma_f32_16x16x32_bf16 v[4:7], v[170:173], v[210:213], v[4:7]
	v_mfma_f32_16x16x32_bf16 v[52:55], v[174:177], v[190:193], v[52:55]
	v_mfma_f32_16x16x32_bf16 v[48:51], v[182:185], v[190:193], v[48:51]
	v_mfma_f32_16x16x32_bf16 v[32:35], v[182:185], v[198:201], v[32:35]
	v_mfma_f32_16x16x32_bf16 v[36:39], v[174:177], v[198:201], v[36:39]
	v_mfma_f32_16x16x32_bf16 v[20:23], v[174:177], v[206:209], v[20:23]
	v_mfma_f32_16x16x32_bf16 v[16:19], v[182:185], v[206:209], v[16:19]
	v_mfma_f32_16x16x32_bf16 v[0:3], v[182:185], v[214:217], v[0:3]
	v_mfma_f32_16x16x32_bf16 v[4:7], v[174:177], v[214:217], v[4:7]
	s_setprio 0
	s_barrier
	s_add_i32 s65, 0, 0x18000
	v_add_u32_e32 v142, s65, v145
	s_add_i32 s66, 0, 0x1c000
	ds_read_b128 v[154:157], v142
	ds_read_b128 v[158:161], v142 offset:1024
	ds_read_b128 v[162:165], v142 offset:2048
	ds_read_b128 v[166:169], v142 offset:3072
	v_add_u32_e32 v142, s66, v145
	ds_read_b128 v[170:173], v142
	ds_read_b128 v[174:177], v142 offset:1024
	ds_read_b128 v[178:181], v142 offset:2048
	ds_read_b128 v[182:185], v142 offset:3072
	s_add_u32 s30, s30, 0x80000
	s_addc_u32 s31, s31, 0
	s_mov_b32 m0, s51
	v_lshl_add_u64 v[228:229], s[30:31], 0, v[134:135]
	ds_read_b128 v[186:189], v151 offset:32768
	ds_read_b128 v[190:193], v151 offset:33792
	ds_read_b128 v[194:197], v151 offset:34816
	ds_read_b128 v[198:201], v151 offset:35840
	ds_read_b128 v[202:205], v151 offset:36864
	ds_read_b128 v[206:209], v151 offset:37888
	ds_read_b128 v[210:213], v151 offset:38912
	ds_read_b128 v[214:217], v151 offset:39936
	global_load_lds_dwordx4 v[228:229], off
	v_lshl_add_u64 v[228:229], s[30:31], 0, v[130:131]
	s_mov_b32 m0, s54
	s_nop 0
	global_load_lds_dwordx4 v[228:229], off
	s_nop 0
	s_waitcnt vmcnt(8)
	s_waitcnt lgkmcnt(0)
	s_barrier
	s_setprio 1
	s_waitcnt lgkmcnt(0)
	v_mfma_f32_16x16x32_bf16 v[124:127], v[154:157], v[186:189], v[124:127]
	v_mfma_f32_16x16x32_bf16 v[120:123], v[162:165], v[186:189], v[120:123]
	v_mfma_f32_16x16x32_bf16 v[104:107], v[162:165], v[194:197], v[104:107]
	v_mfma_f32_16x16x32_bf16 v[108:111], v[154:157], v[194:197], v[108:111]
	v_mfma_f32_16x16x32_bf16 v[92:95], v[154:157], v[202:205], v[92:95]
	v_mfma_f32_16x16x32_bf16 v[88:91], v[162:165], v[202:205], v[88:91]
	v_mfma_f32_16x16x32_bf16 v[72:75], v[162:165], v[210:213], v[72:75]
	v_mfma_f32_16x16x32_bf16 v[76:79], v[154:157], v[210:213], v[76:79]
	v_mfma_f32_16x16x32_bf16 v[124:127], v[158:161], v[190:193], v[124:127]
	v_mfma_f32_16x16x32_bf16 v[120:123], v[166:169], v[190:193], v[120:123]
	v_mfma_f32_16x16x32_bf16 v[104:107], v[166:169], v[198:201], v[104:107]
	v_mfma_f32_16x16x32_bf16 v[108:111], v[158:161], v[198:201], v[108:111]
	v_mfma_f32_16x16x32_bf16 v[92:95], v[158:161], v[206:209], v[92:95]
	v_mfma_f32_16x16x32_bf16 v[88:91], v[166:169], v[206:209], v[88:91]
	v_mfma_f32_16x16x32_bf16 v[72:75], v[166:169], v[214:217], v[72:75]
	v_mfma_f32_16x16x32_bf16 v[76:79], v[158:161], v[214:217], v[76:79]
	s_setprio 0
	s_setprio 1
	v_mfma_f32_16x16x32_bf16 v[116:119], v[170:173], v[186:189], v[116:119]
	v_mfma_f32_16x16x32_bf16 v[112:115], v[178:181], v[186:189], v[112:115]
	v_mfma_f32_16x16x32_bf16 v[96:99], v[178:181], v[194:197], v[96:99]
	v_mfma_f32_16x16x32_bf16 v[100:103], v[170:173], v[194:197], v[100:103]
	v_mfma_f32_16x16x32_bf16 v[84:87], v[170:173], v[202:205], v[84:87]
	v_mfma_f32_16x16x32_bf16 v[80:83], v[178:181], v[202:205], v[80:83]
	v_mfma_f32_16x16x32_bf16 v[64:67], v[178:181], v[210:213], v[64:67]
	v_mfma_f32_16x16x32_bf16 v[68:71], v[170:173], v[210:213], v[68:71]
	v_mfma_f32_16x16x32_bf16 v[116:119], v[174:177], v[190:193], v[116:119]
	v_mfma_f32_16x16x32_bf16 v[112:115], v[182:185], v[190:193], v[112:115]
	v_mfma_f32_16x16x32_bf16 v[96:99], v[182:185], v[198:201], v[96:99]
	v_mfma_f32_16x16x32_bf16 v[100:103], v[174:177], v[198:201], v[100:103]
	v_mfma_f32_16x16x32_bf16 v[84:87], v[174:177], v[206:209], v[84:87]
	v_mfma_f32_16x16x32_bf16 v[80:83], v[182:185], v[206:209], v[80:83]
	v_mfma_f32_16x16x32_bf16 v[64:67], v[182:185], v[214:217], v[64:67]
	v_mfma_f32_16x16x32_bf16 v[68:71], v[174:177], v[214:217], v[68:71]
	s_setprio 0
	s_barrier
; #define PG8_STAGE(bufoff, gbase, voff) do { _Pragma("unroll") for (int _i = 0; _i < 2; ++_i) \
;         __builtin_amdgcn_global_load_lds((const unsigned*)((const char*)(gbase) + (voff)[_i]), (LAS unsigned*)(lds + (bufoff) + ldsw + _i * 8192), 16, 0, 0); } while (0)
; #define PG8_LDA(dst, b, h) do { _Pragma("unroll") for (int m = 0; m < 4; ++m) _Pragma("unroll") for (int k = 0; k < 2; ++k) dst[m][k] = *(const LAS bf16x8*)(lds + PG8_SA(b, h) + aoff + m * 2048 + k * 1024); } while (0)
; #define PG8_MMA(ai, bj, At, Bt) do { __builtin_amdgcn_s_setprio(1); _Pragma("unroll") for (int m = 0; m < 4; ++m) _Pragma("unroll") for (int n = 0; n < 2; ++n) _Pragma("unroll") for (int k = 0; k < 2; ++k) \
;         acc[ai][bj][m][n] = __builtin_amdgcn_mfma_f32_16x16x32_bf16(Bt[n][k], At[m][k], acc[ai][bj][m][n], 0, 0, 0); __builtin_amdgcn_s_setprio(0); } while (0)
; #define PG8_WAIT_V(n) asm volatile("s_waitcnt vmcnt(" #n ")" ::: "memory")
; #define PG8_WAIT_L(n) asm volatile("s_waitcnt lgkmcnt(" #n ")" ::: "memory")
; #define PG8_BAR __builtin_amdgcn_s_barrier()
; #define PG8_SCHED __builtin_amdgcn_sched_barrier(0)
; template <int FIXED_NT  , class Epi, class Sched>
; __device__ __forceinline__ void gemm_phase(LAS unsigned char* lds, const int tid_in, const int lda, const int ldb, const Sched& S, const Epi& E) {
;     ...
;             PG8_LDA(At, 1, 1); PG8_STAGE(PG8_SB(1, 0), b3, voffB); PG8_STAGE(PG8_SB(1, 1), b3 + hstepB, voffB); PG8_STAGE(PG8_SA(1, 0), a3, voffA);
;             PG8_WAIT_V(8); PG8_WAIT_L(0); PG8_BAR; PG8_MMA(1, 0, At, B0); PG8_MMA(1, 1, At, B1); PG8_BAR; PG8_SCHED;
;         }
	s_add_i32 s30, s65, s35
	v_lshl_add_u64 v[218:219], v[218:219], 0, s[8:9]
	s_mov_b32 m0, s30
	ds_read_b128 v[186:189], v151 offset:49152
	ds_read_b128 v[190:193], v151 offset:50176
	ds_read_b128 v[194:197], v151 offset:51200
	ds_read_b128 v[198:201], v151 offset:52224
	ds_read_b128 v[202:205], v151 offset:53248
	ds_read_b128 v[206:209], v151 offset:54272
	ds_read_b128 v[210:213], v151 offset:55296
	ds_read_b128 v[214:217], v151 offset:56320
	global_load_lds_dwordx4 v[218:219], off
	s_add_i32 m0, s30, 0x2000
	s_add_u32 s28, s28, 0x80080
	v_lshl_add_u64 v[218:219], v[220:221], 0, s[8:9]
	s_addc_u32 s29, s29, 0
	s_add_i32 s30, s66, s35
	global_load_lds_dwordx4 v[218:219], off
	v_lshl_add_u64 v[218:219], s[28:29], 0, v[132:133]
	s_mov_b32 m0, s30
	s_nop 0
	global_load_lds_dwordx4 v[218:219], off
	v_lshl_add_u64 v[218:219], s[28:29], 0, v[128:129]
	s_add_i32 m0, s30, 0x2000
	s_nop 0
	global_load_lds_dwordx4 v[218:219], off
	v_lshl_add_u64 v[218:219], v[222:223], 0, s[8:9]
	s_mov_b32 m0, s56
	s_nop 0
	global_load_lds_dwordx4 v[218:219], off
	v_lshl_add_u64 v[218:219], v[226:227], 0, s[8:9]
	s_mov_b32 m0, s57
	s_nop 0
	global_load_lds_dwordx4 v[218:219], off
	s_waitcnt vmcnt(8)
	s_waitcnt lgkmcnt(0)
	s_barrier
	s_setprio 1
	s_waitcnt lgkmcnt(0)
	v_mfma_f32_16x16x32_bf16 v[60:63], v[154:157], v[186:189], v[60:63]
	v_mfma_f32_16x16x32_bf16 v[56:59], v[162:165], v[186:189], v[56:59]
	v_mfma_f32_16x16x32_bf16 v[40:43], v[162:165], v[194:197], v[40:43]
	v_mfma_f32_16x16x32_bf16 v[44:47], v[154:157], v[194:197], v[44:47]
	v_mfma_f32_16x16x32_bf16 v[28:31], v[154:157], v[202:205], v[28:31]
	v_mfma_f32_16x16x32_bf16 v[24:27], v[162:165], v[202:205], v[24:27]
	v_mfma_f32_16x16x32_bf16 v[8:11], v[162:165], v[210:213], v[8:11]
	v_mfma_f32_16x16x32_bf16 v[12:15], v[154:157], v[210:213], v[12:15]
	v_mfma_f32_16x16x32_bf16 v[60:63], v[158:161], v[190:193], v[60:63]
	v_mfma_f32_16x16x32_bf16 v[56:59], v[166:169], v[190:193], v[56:59]
	v_mfma_f32_16x16x32_bf16 v[40:43], v[166:169], v[198:201], v[40:43]
	v_mfma_f32_16x16x32_bf16 v[44:47], v[158:161], v[198:201], v[44:47]
	v_mfma_f32_16x16x32_bf16 v[28:31], v[158:161], v[206:209], v[28:31]
	v_mfma_f32_16x16x32_bf16 v[24:27], v[166:169], v[206:209], v[24:27]
	v_mfma_f32_16x16x32_bf16 v[8:11], v[166:169], v[214:217], v[8:11]
	v_mfma_f32_16x16x32_bf16 v[12:15], v[158:161], v[214:217], v[12:15]
	s_setprio 0
	s_setprio 1
	v_mfma_f32_16x16x32_bf16 v[52:55], v[170:173], v[186:189], v[52:55]
	v_mfma_f32_16x16x32_bf16 v[48:51], v[178:181], v[186:189], v[48:51]
	v_mfma_f32_16x16x32_bf16 v[32:35], v[178:181], v[194:197], v[32:35]
	v_mfma_f32_16x16x32_bf16 v[36:39], v[170:173], v[194:197], v[36:39]
	v_mfma_f32_16x16x32_bf16 v[20:23], v[170:173], v[202:205], v[20:23]
	v_mfma_f32_16x16x32_bf16 v[16:19], v[178:181], v[202:205], v[16:19]
	v_mfma_f32_16x16x32_bf16 v[0:3], v[178:181], v[210:213], v[0:3]
	v_mfma_f32_16x16x32_bf16 v[4:7], v[170:173], v[210:213], v[4:7]
	v_mfma_f32_16x16x32_bf16 v[52:55], v[174:177], v[190:193], v[52:55]
	v_mfma_f32_16x16x32_bf16 v[48:51], v[182:185], v[190:193], v[48:51]
	v_mfma_f32_16x16x32_bf16 v[32:35], v[182:185], v[198:201], v[32:35]
	v_mfma_f32_16x16x32_bf16 v[36:39], v[174:177], v[198:201], v[36:39]
	v_mfma_f32_16x16x32_bf16 v[20:23], v[174:177], v[206:209], v[20:23]
	v_mfma_f32_16x16x32_bf16 v[16:19], v[182:185], v[206:209], v[16:19]
	v_mfma_f32_16x16x32_bf16 v[0:3], v[182:185], v[214:217], v[0:3]
	v_mfma_f32_16x16x32_bf16 v[4:7], v[174:177], v[214:217], v[4:7]
	s_setprio 0
	s_barrier
	s_add_u32 s24, s24, 0x100
	s_addc_u32 s25, s25, 0
	s_add_u32 s15, s15, 0x100
	s_addc_u32 s63, s63, 0
	s_cmp_ge_i32 s64, s27
	s_mov_b32 s28, s64
	s_cbranch_scc0 .LBB0_1178
	s_and_b64 vcc, exec, s[12:13]
	s_cbranch_vccz .LBB0_1181

; #define PG8_STAGE(bufoff, gbase, voff) do { _Pragma("unroll") for (int _i = 0; _i < 2; ++_i) \
;         __builtin_amdgcn_global_load_lds((const unsigned*)((const char*)(gbase) + (voff)[_i]), (LAS unsigned*)(lds + (bufoff) + ldsw + _i * 8192), 16, 0, 0); } while (0)
; #define PG8_LDA(dst, b, h) do { _Pragma("unroll") for (int m = 0; m < 4; ++m) _Pragma("unroll") for (int k = 0; k < 2; ++k) dst[m][k] = *(const LAS bf16x8*)(lds + PG8_SA(b, h) + aoff + m * 2048 + k * 1024); } while (0)
; #define PG8_LDB(dst, b, h) do { _Pragma("unroll") for (int n = 0; n < 2; ++n) _Pragma("unroll") for (int k = 0; k < 2; ++k) dst[n][k] = *(const LAS bf16x8*)(lds + PG8_SB(b, h) + boff + n * 2048 + k * 1024); } while (0)
; #define PG8_MMA(ai, bj, At, Bt) do { __builtin_amdgcn_s_setprio(1); _Pragma("unroll") for (int m = 0; m < 4; ++m) _Pragma("unroll") for (int n = 0; n < 2; ++n) _Pragma("unroll") for (int k = 0; k < 2; ++k) \
;         acc[ai][bj][m][n] = __builtin_amdgcn_mfma_f32_16x16x32_bf16(Bt[n][k], At[m][k], acc[ai][bj][m][n], 0, 0, 0); __builtin_amdgcn_s_setprio(0); } while (0)
; #define PG8_WAIT_V(n) asm volatile("s_waitcnt vmcnt(" #n ")" ::: "memory")
; #define PG8_WAIT_L(n) asm volatile("s_waitcnt lgkmcnt(" #n ")" ::: "memory")
; #define PG8_BAR __builtin_amdgcn_s_barrier()
; #define PG8_SCHED __builtin_amdgcn_sched_barrier(0)
; template <int FIXED_NT  , class Epi, class Sched>
; __device__ __forceinline__ void gemm_phase(LAS unsigned char* lds, const int tid_in, const int lda, const int ldb, const Sched& S, const Epi& E) {
;     ...
;         for (int t = 0; t < nt; t += 2) {
;             const bool last = (t == nt - 2);
;             const char* a1 = cA + (size_t)(t + 1) * kstep;
;             const char* a2 = last ? nA : cA + (size_t)(t + 2) * kstep; const char* b2 = last ? nB : cB + (size_t)(t + 2) * kstep;
;             const char* a3 = a2 + kstep; const char* b3 = b2 + kstep;
;             PG8_LDB(B0, 0, 0); PG8_LDB(B1, 0, 1); PG8_SCHED; PG8_LDA(At, 0, 0); PG8_STAGE(PG8_SA(1, 1), a1 + hstepA, voffA);
;             PG8_WAIT_V(8); PG8_WAIT_L(0); PG8_BAR; PG8_MMA(0, 0, At, B0); PG8_MMA(0, 1, At, B1); PG8_BAR; PG8_SCHED;
;             PG8_LDA(At, 0, 1); PG8_STAGE(PG8_SB(0, 0), b2, voffB); PG8_STAGE(PG8_SB(0, 1), b2 + hstepB, voffB); PG8_STAGE(PG8_SA(0, 0), a2, voffA);
.LBB0_1273:
	ds_read_b128 v[128:131], v186
	ds_read_b128 v[132:135], v186 offset:1024
	ds_read_b128 v[136:139], v186 offset:2048
	ds_read_b128 v[140:143], v186 offset:3072
	ds_read_b128 v[144:147], v187
	ds_read_b128 v[148:151], v187 offset:1024
	ds_read_b128 v[152:155], v187 offset:2048
	ds_read_b128 v[170:173], v187 offset:3072
	s_add_i32 s68, s24, 2
	s_add_u32 s22, s4, 0x100
	s_addc_u32 s23, s5, 0
	s_cmp_eq_u32 s65, s24
	s_cselect_b32 s24, s64, s66
	s_cselect_b32 s29, s61, s23
	s_cselect_b32 s28, s62, s22
	s_cselect_b32 s25, s63, s67
	v_lshl_add_u64 v[178:179], s[4:5], 0, v[166:167]
	s_add_i32 m0, s27, 0xc000
	ds_read_b128 v[174:177], v188
	ds_read_b128 v[190:193], v188 offset:1024
	ds_read_b128 v[194:197], v188 offset:2048
	ds_read_b128 v[198:201], v188 offset:3072
	ds_read_b128 v[202:205], v188 offset:4096
	ds_read_b128 v[206:209], v188 offset:5120
	ds_read_b128 v[210:213], v188 offset:6144
	ds_read_b128 v[214:217], v188 offset:7168
	global_load_lds_dwordx4 v[178:179], off
	v_lshl_add_u64 v[178:179], s[4:5], 0, v[168:169]
	s_add_i32 m0, s27, 0xe000
	s_nop 0
	global_load_lds_dwordx4 v[178:179], off
	s_nop 0
	s_waitcnt vmcnt(8)
	s_waitcnt lgkmcnt(0)
	s_barrier
	s_setprio 1
	s_waitcnt lgkmcnt(0)
	v_mfma_f32_16x16x32_bf16 v[124:127], v[128:131], v[174:177], v[124:127]
	v_mfma_f32_16x16x32_bf16 v[120:123], v[136:139], v[174:177], v[120:123]
	v_mfma_f32_16x16x32_bf16 v[104:107], v[136:139], v[194:197], v[104:107]
	v_mfma_f32_16x16x32_bf16 v[108:111], v[128:131], v[194:197], v[108:111]
	v_mfma_f32_16x16x32_bf16 v[92:95], v[128:131], v[202:205], v[92:95]
	v_mfma_f32_16x16x32_bf16 v[88:91], v[136:139], v[202:205], v[88:91]
	v_mfma_f32_16x16x32_bf16 v[72:75], v[136:139], v[210:213], v[72:75]
	v_mfma_f32_16x16x32_bf16 v[76:79], v[128:131], v[210:213], v[76:79]
	v_mfma_f32_16x16x32_bf16 v[124:127], v[132:135], v[190:193], v[124:127]
	v_mfma_f32_16x16x32_bf16 v[120:123], v[140:143], v[190:193], v[120:123]
	v_mfma_f32_16x16x32_bf16 v[104:107], v[140:143], v[198:201], v[104:107]
	v_mfma_f32_16x16x32_bf16 v[108:111], v[132:135], v[198:201], v[108:111]
	v_mfma_f32_16x16x32_bf16 v[92:95], v[132:135], v[206:209], v[92:95]
	v_mfma_f32_16x16x32_bf16 v[88:91], v[140:143], v[206:209], v[88:91]
	v_mfma_f32_16x16x32_bf16 v[72:75], v[140:143], v[214:217], v[72:75]
	v_mfma_f32_16x16x32_bf16 v[76:79], v[132:135], v[214:217], v[76:79]
	s_setprio 0
	s_setprio 1
	v_mfma_f32_16x16x32_bf16 v[116:119], v[144:147], v[174:177], v[116:119]
	v_mfma_f32_16x16x32_bf16 v[112:115], v[152:155], v[174:177], v[112:115]
	v_mfma_f32_16x16x32_bf16 v[96:99], v[152:155], v[194:197], v[96:99]
	v_mfma_f32_16x16x32_bf16 v[100:103], v[144:147], v[194:197], v[100:103]
	v_mfma_f32_16x16x32_bf16 v[84:87], v[144:147], v[202:205], v[84:87]
	v_mfma_f32_16x16x32_bf16 v[80:83], v[152:155], v[202:205], v[80:83]
	v_mfma_f32_16x16x32_bf16 v[64:67], v[152:155], v[210:213], v[64:67]
	v_mfma_f32_16x16x32_bf16 v[68:71], v[144:147], v[210:213], v[68:71]
	v_mfma_f32_16x16x32_bf16 v[116:119], v[148:151], v[190:193], v[116:119]
	v_mfma_f32_16x16x32_bf16 v[112:115], v[170:173], v[190:193], v[112:115]
	v_mfma_f32_16x16x32_bf16 v[96:99], v[170:173], v[198:201], v[96:99]
	v_mfma_f32_16x16x32_bf16 v[100:103], v[148:151], v[198:201], v[100:103]
	v_mfma_f32_16x16x32_bf16 v[84:87], v[148:151], v[206:209], v[84:87]
	v_mfma_f32_16x16x32_bf16 v[80:83], v[170:173], v[206:209], v[80:83]
	v_mfma_f32_16x16x32_bf16 v[64:67], v[170:173], v[214:217], v[64:67]
	v_mfma_f32_16x16x32_bf16 v[68:71], v[148:151], v[214:217], v[68:71]
	s_setprio 0
	s_barrier
	s_add_i32 s4, s50, s3
	v_lshl_add_u64 v[178:179], s[24:25], 0, v[158:159]
	s_mov_b32 m0, s4
	ds_read_b128 v[174:177], v188 offset:16384
	ds_read_b128 v[190:193], v188 offset:17408
	ds_read_b128 v[194:197], v188 offset:18432
	ds_read_b128 v[198:201], v188 offset:19456
	ds_read_b128 v[202:205], v188 offset:20480
	ds_read_b128 v[206:209], v188 offset:21504
	ds_read_b128 v[210:213], v188 offset:22528
	ds_read_b128 v[214:217], v188 offset:23552
	global_load_lds_dwordx4 v[178:179], off
	s_add_i32 m0, s4, 0x2000
	s_add_u32 s4, s24, 0x160000
	v_lshl_add_u64 v[218:219], s[24:25], 0, v[162:163]
	s_addc_u32 s5, s25, 0
	s_add_i32 s69, s51, s3
	global_load_lds_dwordx4 v[218:219], off
	v_lshl_add_u64 v[220:221], s[4:5], 0, v[158:159]
	s_mov_b32 m0, s69
	v_lshl_add_u64 v[222:223], s[28:29], 0, v[160:161]
	global_load_lds_dwordx4 v[220:221], off
	v_lshl_add_u64 v[220:221], s[4:5], 0, v[162:163]
	s_add_i32 m0, s69, 0x2000
	s_nop 0
	global_load_lds_dwordx4 v[220:221], off
	v_lshl_add_u64 v[220:221], s[28:29], 0, v[156:157]
	s_mov_b32 m0, s27
	s_nop 0
	global_load_lds_dwordx4 v[220:221], off
	s_mov_b32 m0, s30
	s_nop 0
	global_load_lds_dwordx4 v[222:223], off
	s_nop 0
	s_waitcnt vmcnt(8)
	s_waitcnt lgkmcnt(0)
	s_barrier
; #define PG8_STAGE(bufoff, gbase, voff) do { _Pragma("unroll") for (int _i = 0; _i < 2; ++_i) \
;         __builtin_amdgcn_global_load_lds((const unsigned*)((const char*)(gbase) + (voff)[_i]), (LAS unsigned*)(lds + (bufoff) + ldsw + _i * 8192), 16, 0, 0); } while (0)
; #define PG8_LDA(dst, b, h) do { _Pragma("unroll") for (int m = 0; m < 4; ++m) _Pragma("unroll") for (int k = 0; k < 2; ++k) dst[m][k] = *(const LAS bf16x8*)(lds + PG8_SA(b, h) + aoff + m * 2048 + k * 1024); } while (0)
; #define PG8_LDB(dst, b, h) do { _Pragma("unroll") for (int n = 0; n < 2; ++n) _Pragma("unroll") for (int k = 0; k < 2; ++k) dst[n][k] = *(const LAS bf16x8*)(lds + PG8_SB(b, h) + boff + n * 2048 + k * 1024); } while (0)
; #define PG8_MMA(ai, bj, At, Bt) do { __builtin_amdgcn_s_setprio(1); _Pragma("unroll") for (int m = 0; m < 4; ++m) _Pragma("unroll") for (int n = 0; n < 2; ++n) _Pragma("unroll") for (int k = 0; k < 2; ++k) \
;         acc[ai][bj][m][n] = __builtin_amdgcn_mfma_f32_16x16x32_bf16(Bt[n][k], At[m][k], acc[ai][bj][m][n], 0, 0, 0); __builtin_amdgcn_s_setprio(0); } while (0)
; #define PG8_WAIT_V(n) asm volatile("s_waitcnt vmcnt(" #n ")" ::: "memory")
; #define PG8_WAIT_L(n) asm volatile("s_waitcnt lgkmcnt(" #n ")" ::: "memory")
; #define PG8_BAR __builtin_amdgcn_s_barrier()
; #define PG8_SCHED __builtin_amdgcn_sched_barrier(0)
; template <int FIXED_NT  , class Epi, class Sched>
; __device__ __forceinline__ void gemm_phase(LAS unsigned char* lds, const int tid_in, const int lda, const int ldb, const Sched& S, const Epi& E) {
;     ...
;             PG8_WAIT_V(8); PG8_WAIT_L(0); PG8_BAR; PG8_MMA(1, 0, At, B0); PG8_MMA(1, 1, At, B1); PG8_BAR; PG8_SCHED;
;             PG8_LDB(B0, 1, 0); PG8_LDB(B1, 1, 1); PG8_SCHED; PG8_LDA(At, 1, 0); PG8_STAGE(PG8_SA(0, 1), a2 + hstepA, voffA);
;             PG8_WAIT_V(8); PG8_WAIT_L(0); PG8_BAR; PG8_MMA(0, 0, At, B0); PG8_MMA(0, 1, At, B1); PG8_BAR; PG8_SCHED;
	s_setprio 1
	s_waitcnt lgkmcnt(0)
	v_mfma_f32_16x16x32_bf16 v[60:63], v[128:131], v[174:177], v[60:63]
	v_mfma_f32_16x16x32_bf16 v[56:59], v[136:139], v[174:177], v[56:59]
	v_mfma_f32_16x16x32_bf16 v[40:43], v[136:139], v[194:197], v[40:43]
	v_mfma_f32_16x16x32_bf16 v[44:47], v[128:131], v[194:197], v[44:47]
	v_mfma_f32_16x16x32_bf16 v[28:31], v[128:131], v[202:205], v[28:31]
	v_mfma_f32_16x16x32_bf16 v[24:27], v[136:139], v[202:205], v[24:27]
	v_mfma_f32_16x16x32_bf16 v[8:11], v[136:139], v[210:213], v[8:11]
	v_mfma_f32_16x16x32_bf16 v[12:15], v[128:131], v[210:213], v[12:15]
	v_mfma_f32_16x16x32_bf16 v[60:63], v[132:135], v[190:193], v[60:63]
	v_mfma_f32_16x16x32_bf16 v[56:59], v[140:143], v[190:193], v[56:59]
	v_mfma_f32_16x16x32_bf16 v[40:43], v[140:143], v[198:201], v[40:43]
	v_mfma_f32_16x16x32_bf16 v[44:47], v[132:135], v[198:201], v[44:47]
	v_mfma_f32_16x16x32_bf16 v[28:31], v[132:135], v[206:209], v[28:31]
	v_mfma_f32_16x16x32_bf16 v[24:27], v[140:143], v[206:209], v[24:27]
	v_mfma_f32_16x16x32_bf16 v[8:11], v[140:143], v[214:217], v[8:11]
	v_mfma_f32_16x16x32_bf16 v[12:15], v[132:135], v[214:217], v[12:15]
	s_setprio 0
	s_setprio 1
	v_mfma_f32_16x16x32_bf16 v[52:55], v[144:147], v[174:177], v[52:55]
	v_mfma_f32_16x16x32_bf16 v[48:51], v[152:155], v[174:177], v[48:51]
	v_mfma_f32_16x16x32_bf16 v[32:35], v[152:155], v[194:197], v[32:35]
	v_mfma_f32_16x16x32_bf16 v[36:39], v[144:147], v[194:197], v[36:39]
	v_mfma_f32_16x16x32_bf16 v[20:23], v[144:147], v[202:205], v[20:23]
	v_mfma_f32_16x16x32_bf16 v[16:19], v[152:155], v[202:205], v[16:19]
	v_mfma_f32_16x16x32_bf16 v[0:3], v[152:155], v[210:213], v[0:3]
	v_mfma_f32_16x16x32_bf16 v[4:7], v[144:147], v[210:213], v[4:7]
	v_mfma_f32_16x16x32_bf16 v[52:55], v[148:151], v[190:193], v[52:55]
	v_mfma_f32_16x16x32_bf16 v[48:51], v[170:173], v[190:193], v[48:51]
	v_mfma_f32_16x16x32_bf16 v[32:35], v[170:173], v[198:201], v[32:35]
	v_mfma_f32_16x16x32_bf16 v[36:39], v[148:151], v[198:201], v[36:39]
	v_mfma_f32_16x16x32_bf16 v[20:23], v[148:151], v[206:209], v[20:23]
	v_mfma_f32_16x16x32_bf16 v[16:19], v[170:173], v[206:209], v[16:19]
	v_mfma_f32_16x16x32_bf16 v[0:3], v[170:173], v[214:217], v[0:3]
	v_mfma_f32_16x16x32_bf16 v[4:7], v[148:151], v[214:217], v[4:7]
	s_setprio 0
	s_barrier
	s_add_i32 s69, 0, 0x18000
	s_add_i32 s70, 0, 0x1c000
	v_add_u32_e32 v140, s69, v181
	v_add_u32_e32 v170, s70, v181
	ds_read_b128 v[128:131], v140
	ds_read_b128 v[132:135], v140 offset:1024
	ds_read_b128 v[136:139], v140 offset:2048
	ds_read_b128 v[140:143], v140 offset:3072
	ds_read_b128 v[144:147], v170
	ds_read_b128 v[148:151], v170 offset:1024
	ds_read_b128 v[152:155], v170 offset:2048
	ds_read_b128 v[170:173], v170 offset:3072
	s_add_u32 s4, s28, 0x160000
	s_addc_u32 s5, s29, 0
	s_mov_b32 m0, s31
	v_lshl_add_u64 v[226:227], s[4:5], 0, v[156:157]
	ds_read_b128 v[174:177], v188 offset:32768
	ds_read_b128 v[190:193], v188 offset:33792
	ds_read_b128 v[194:197], v188 offset:34816
	ds_read_b128 v[198:201], v188 offset:35840
	ds_read_b128 v[202:205], v188 offset:36864
	ds_read_b128 v[206:209], v188 offset:37888
	ds_read_b128 v[210:213], v188 offset:38912
	ds_read_b128 v[214:217], v188 offset:39936
	global_load_lds_dwordx4 v[226:227], off
	v_lshl_add_u64 v[226:227], s[4:5], 0, v[160:161]
	s_mov_b32 m0, s35
	s_nop 0
	global_load_lds_dwordx4 v[226:227], off
	s_nop 0
	s_waitcnt vmcnt(8)
	s_waitcnt lgkmcnt(0)
	s_barrier
	s_setprio 1
	s_waitcnt lgkmcnt(0)
	v_mfma_f32_16x16x32_bf16 v[124:127], v[128:131], v[174:177], v[124:127]
	v_mfma_f32_16x16x32_bf16 v[120:123], v[136:139], v[174:177], v[120:123]
	v_mfma_f32_16x16x32_bf16 v[104:107], v[136:139], v[194:197], v[104:107]
	v_mfma_f32_16x16x32_bf16 v[108:111], v[128:131], v[194:197], v[108:111]
	v_mfma_f32_16x16x32_bf16 v[92:95], v[128:131], v[202:205], v[92:95]
	v_mfma_f32_16x16x32_bf16 v[88:91], v[136:139], v[202:205], v[88:91]
	v_mfma_f32_16x16x32_bf16 v[72:75], v[136:139], v[210:213], v[72:75]
	v_mfma_f32_16x16x32_bf16 v[76:79], v[128:131], v[210:213], v[76:79]
	v_mfma_f32_16x16x32_bf16 v[124:127], v[132:135], v[190:193], v[124:127]
	v_mfma_f32_16x16x32_bf16 v[120:123], v[140:143], v[190:193], v[120:123]
	v_mfma_f32_16x16x32_bf16 v[104:107], v[140:143], v[198:201], v[104:107]
	v_mfma_f32_16x16x32_bf16 v[108:111], v[132:135], v[198:201], v[108:111]
	v_mfma_f32_16x16x32_bf16 v[92:95], v[132:135], v[206:209], v[92:95]
	v_mfma_f32_16x16x32_bf16 v[88:91], v[140:143], v[206:209], v[88:91]
	v_mfma_f32_16x16x32_bf16 v[72:75], v[140:143], v[214:217], v[72:75]
	v_mfma_f32_16x16x32_bf16 v[76:79], v[132:135], v[214:217], v[76:79]
	s_setprio 0
	s_setprio 1
	v_mfma_f32_16x16x32_bf16 v[116:119], v[144:147], v[174:177], v[116:119]
	v_mfma_f32_16x16x32_bf16 v[112:115], v[152:155], v[174:177], v[112:115]
	v_mfma_f32_16x16x32_bf16 v[96:99], v[152:155], v[194:197], v[96:99]
	v_mfma_f32_16x16x32_bf16 v[100:103], v[144:147], v[194:197], v[100:103]
	v_mfma_f32_16x16x32_bf16 v[84:87], v[144:147], v[202:205], v[84:87]
	v_mfma_f32_16x16x32_bf16 v[80:83], v[152:155], v[202:205], v[80:83]
	v_mfma_f32_16x16x32_bf16 v[64:67], v[152:155], v[210:213], v[64:67]
	v_mfma_f32_16x16x32_bf16 v[68:71], v[144:147], v[210:213], v[68:71]
	v_mfma_f32_16x16x32_bf16 v[116:119], v[148:151], v[190:193], v[116:119]
	v_mfma_f32_16x16x32_bf16 v[112:115], v[170:173], v[190:193], v[112:115]
	v_mfma_f32_16x16x32_bf16 v[96:99], v[170:173], v[198:201], v[96:99]
	v_mfma_f32_16x16x32_bf16 v[100:103], v[148:151], v[198:201], v[100:103]
	v_mfma_f32_16x16x32_bf16 v[84:87], v[148:151], v[206:209], v[84:87]
	v_mfma_f32_16x16x32_bf16 v[80:83], v[170:173], v[206:209], v[80:83]
	v_mfma_f32_16x16x32_bf16 v[64:67], v[170:173], v[214:217], v[64:67]
	v_mfma_f32_16x16x32_bf16 v[68:71], v[148:151], v[214:217], v[68:71]
	s_setprio 0
	s_barrier
; #define PG8_STAGE(bufoff, gbase, voff) do { _Pragma("unroll") for (int _i = 0; _i < 2; ++_i) \
;         __builtin_amdgcn_global_load_lds((const unsigned*)((const char*)(gbase) + (voff)[_i]), (LAS unsigned*)(lds + (bufoff) + ldsw + _i * 8192), 16, 0, 0); } while (0)
; #define PG8_LDA(dst, b, h) do { _Pragma("unroll") for (int m = 0; m < 4; ++m) _Pragma("unroll") for (int k = 0; k < 2; ++k) dst[m][k] = *(const LAS bf16x8*)(lds + PG8_SA(b, h) + aoff + m * 2048 + k * 1024); } while (0)
; #define PG8_MMA(ai, bj, At, Bt) do { __builtin_amdgcn_s_setprio(1); _Pragma("unroll") for (int m = 0; m < 4; ++m) _Pragma("unroll") for (int n = 0; n < 2; ++n) _Pragma("unroll") for (int k = 0; k < 2; ++k) \
;         acc[ai][bj][m][n] = __builtin_amdgcn_mfma_f32_16x16x32_bf16(Bt[n][k], At[m][k], acc[ai][bj][m][n], 0, 0, 0); __builtin_amdgcn_s_setprio(0); } while (0)
; #define PG8_WAIT_V(n) asm volatile("s_waitcnt vmcnt(" #n ")" ::: "memory")
; #define PG8_WAIT_L(n) asm volatile("s_waitcnt lgkmcnt(" #n ")" ::: "memory")
; #define PG8_BAR __builtin_amdgcn_s_barrier()
; #define PG8_SCHED __builtin_amdgcn_sched_barrier(0)
; template <int FIXED_NT  , class Epi, class Sched>
; __device__ __forceinline__ void gemm_phase(LAS unsigned char* lds, const int tid_in, const int lda, const int ldb, const Sched& S, const Epi& E) {
;     ...
;             PG8_LDA(At, 1, 1); PG8_STAGE(PG8_SB(1, 0), b3, voffB); PG8_STAGE(PG8_SB(1, 1), b3 + hstepB, voffB); PG8_STAGE(PG8_SA(1, 0), a3, voffA);
;             PG8_WAIT_V(8); PG8_WAIT_L(0); PG8_BAR; PG8_MMA(1, 0, At, B0); PG8_MMA(1, 1, At, B1); PG8_BAR; PG8_SCHED;
;         }
	s_add_i32 s4, s69, s3
	v_lshl_add_u64 v[178:179], v[178:179], 0, s[10:11]
	s_mov_b32 m0, s4
	ds_read_b128 v[174:177], v188 offset:49152
	ds_read_b128 v[190:193], v188 offset:50176
	ds_read_b128 v[194:197], v188 offset:51200
	ds_read_b128 v[198:201], v188 offset:52224
	ds_read_b128 v[202:205], v188 offset:53248
	ds_read_b128 v[206:209], v188 offset:54272
	ds_read_b128 v[210:213], v188 offset:55296
	ds_read_b128 v[214:217], v188 offset:56320
	global_load_lds_dwordx4 v[178:179], off
	s_add_i32 m0, s4, 0x2000
	s_add_u32 s4, s24, 0x160080
	v_lshl_add_u64 v[178:179], v[218:219], 0, s[10:11]
	s_addc_u32 s5, s25, 0
	s_add_i32 s24, s70, s3
	global_load_lds_dwordx4 v[178:179], off
	v_lshl_add_u64 v[178:179], s[4:5], 0, v[158:159]
	s_mov_b32 m0, s24
	s_nop 0
	global_load_lds_dwordx4 v[178:179], off
	v_lshl_add_u64 v[178:179], s[4:5], 0, v[162:163]
	s_add_i32 m0, s24, 0x2000
	s_nop 0
	global_load_lds_dwordx4 v[178:179], off
	v_lshl_add_u64 v[178:179], v[220:221], 0, s[10:11]
	s_mov_b32 m0, s44
	s_nop 0
	global_load_lds_dwordx4 v[178:179], off
	v_lshl_add_u64 v[178:179], v[222:223], 0, s[10:11]
	s_mov_b32 m0, s45
	s_nop 0
	global_load_lds_dwordx4 v[178:179], off
	s_waitcnt vmcnt(8)
	s_waitcnt lgkmcnt(0)
	s_barrier
	s_setprio 1
	s_waitcnt lgkmcnt(0)
	v_mfma_f32_16x16x32_bf16 v[60:63], v[128:131], v[174:177], v[60:63]
	v_mfma_f32_16x16x32_bf16 v[56:59], v[136:139], v[174:177], v[56:59]
	v_mfma_f32_16x16x32_bf16 v[40:43], v[136:139], v[194:197], v[40:43]
	v_mfma_f32_16x16x32_bf16 v[44:47], v[128:131], v[194:197], v[44:47]
	v_mfma_f32_16x16x32_bf16 v[28:31], v[128:131], v[202:205], v[28:31]
	v_mfma_f32_16x16x32_bf16 v[24:27], v[136:139], v[202:205], v[24:27]
	v_mfma_f32_16x16x32_bf16 v[8:11], v[136:139], v[210:213], v[8:11]
	v_mfma_f32_16x16x32_bf16 v[12:15], v[128:131], v[210:213], v[12:15]
	v_mfma_f32_16x16x32_bf16 v[60:63], v[132:135], v[190:193], v[60:63]
	v_mfma_f32_16x16x32_bf16 v[56:59], v[140:143], v[190:193], v[56:59]
	v_mfma_f32_16x16x32_bf16 v[40:43], v[140:143], v[198:201], v[40:43]
	v_mfma_f32_16x16x32_bf16 v[44:47], v[132:135], v[198:201], v[44:47]
	v_mfma_f32_16x16x32_bf16 v[28:31], v[132:135], v[206:209], v[28:31]
	v_mfma_f32_16x16x32_bf16 v[24:27], v[140:143], v[206:209], v[24:27]
	v_mfma_f32_16x16x32_bf16 v[8:11], v[140:143], v[214:217], v[8:11]
	v_mfma_f32_16x16x32_bf16 v[12:15], v[132:135], v[214:217], v[12:15]
	s_setprio 0
	s_setprio 1
	v_mfma_f32_16x16x32_bf16 v[52:55], v[144:147], v[174:177], v[52:55]
	v_mfma_f32_16x16x32_bf16 v[48:51], v[152:155], v[174:177], v[48:51]
	v_mfma_f32_16x16x32_bf16 v[32:35], v[152:155], v[194:197], v[32:35]
	v_mfma_f32_16x16x32_bf16 v[36:39], v[144:147], v[194:197], v[36:39]
	v_mfma_f32_16x16x32_bf16 v[20:23], v[144:147], v[202:205], v[20:23]
	v_mfma_f32_16x16x32_bf16 v[16:19], v[152:155], v[202:205], v[16:19]
	v_mfma_f32_16x16x32_bf16 v[0:3], v[152:155], v[210:213], v[0:3]
	v_mfma_f32_16x16x32_bf16 v[4:7], v[144:147], v[210:213], v[4:7]
	v_mfma_f32_16x16x32_bf16 v[52:55], v[148:151], v[190:193], v[52:55]
	v_mfma_f32_16x16x32_bf16 v[48:51], v[170:173], v[190:193], v[48:51]
	v_mfma_f32_16x16x32_bf16 v[32:35], v[170:173], v[198:201], v[32:35]
	v_mfma_f32_16x16x32_bf16 v[36:39], v[148:151], v[198:201], v[36:39]
	v_mfma_f32_16x16x32_bf16 v[20:23], v[148:151], v[206:209], v[20:23]
	v_mfma_f32_16x16x32_bf16 v[16:19], v[170:173], v[206:209], v[16:19]
	v_mfma_f32_16x16x32_bf16 v[0:3], v[170:173], v[214:217], v[0:3]
	v_mfma_f32_16x16x32_bf16 v[4:7], v[148:151], v[214:217], v[4:7]
	s_setprio 0
	s_barrier
	s_add_u32 s66, s66, 0x100
	s_addc_u32 s67, s67, 0
	s_cmp_ge_i32 s68, s60
	s_mov_b64 s[4:5], s[22:23]
	s_mov_b32 s24, s68
	s_cbranch_scc0 .LBB0_1273
	s_and_b64 vcc, exec, s[12:13]
	s_cbranch_vccz .LBB0_1276
